# tail split: half units get their own K-loop and epilogue copies (out of line); the full-unit path is the baseline's plus one compare/branch per unit
# speedup vs baseline: 1.0058x; 1.0039x over previous
.LBB0_1717:
	s_or_b64 exec, exec, s[6:7]
	s_add_i32 s3, 0, 0x22080
	v_mov_b32_e32 v0, s3
	s_waitcnt lgkmcnt(0)
	s_barrier
	ds_read_b32 v0, v0
	s_load_dword s3, s[0:1], 0x230
	s_add_u32 s10, s0, 0x230
	s_addc_u32 s11, s1, 0
	v_readfirstlane_b32 s54, v209
	s_waitcnt lgkmcnt(0)
	v_cmp_ge_i32_e32 vcc, s2, v0
	v_readfirstlane_b32 s6, v0
	s_mov_b32 s92, s6
	s_lshr_b32 s93, s92, 8
	s_and_b32 s94, s92, 0xff
	s_sub_i32 s95, 0x100, s94
	s_min_u32 s95, s95, s94
	s_cmp_eq_u32 s3, 0x100
	s_cselect_b32 s93, s93, 0x7fffffff
	s_cmp_eq_u32 s93, 0
	s_cselect_b32 s93, 0x7fffffff, s93
	s_mov_b32 s90, 3
	s_mov_b32 s91, 3
	s_cbranch_vccnz .LBB0_1755
	s_ashr_i32 s7, s6, 31
	s_lshr_b32 s8, s7, 29
	s_add_i32 s8, s6, s8
	s_ashr_i32 s55, s8, 3
	s_and_b32 s8, s8, -8
	s_ashr_i32 s57, s2, 31
	s_sub_i32 s56, s6, s8
	s_lshr_b32 s8, s57, 29
	s_add_i32 s13, s2, s8
	s_and_b32 s8, s13, -8
	s_sub_i32 s12, s2, s8
	s_add_i32 s58, s55, 1
	s_cmp_ge_i32 s12, s56
	s_mul_i32 s59, s58, s56
	s_cbranch_scc0 .LBB0_1720
	s_sub_i32 s8, s12, s56
	s_mul_i32 s8, s8, s55
	s_add_i32 s20, s8, s59
	s_ashr_i32 s8, s13, 3
	s_cbranch_execz .LBB0_1721
	s_branch .LBB0_1722

.LBB0_1732:
	v_mul_f32_e32 v129, 0xbfb8aa3b, v124
	v_exp_f32_e32 v132, v129
	s_ashr_i32 s6, s82, 1
	v_add_u32_e32 v130, s6, v212
	v_add_u32_e32 v128, v198, v210
	v_add_f32_e32 v132, 1.0, v132
	v_rcp_f32_e32 v134, v132
	v_ashrrev_i32_e32 v129, 31, v128
	v_lshlrev_b64 v[128:129], 11, v[128:129]
	v_ashrrev_i32_e32 v131, 31, v130
	v_lshl_add_u64 v[128:129], s[14:15], 0, v[128:129]
	v_lshl_add_u64 v[128:129], v[130:131], 1, v[128:129]
	v_mul_f32_e32 v135, 0xbfb8aa3b, v125
	v_exp_f32_e32 v135, v135
	s_nop 0
	v_add_f32_e32 v133, 1.0, v135
	v_rcp_f32_e32 v136, v133
	v_mul_f32_e32 v130, v124, v134
	v_mov_b32_e32 v124, v130
	v_mul_f32_e32 v120, v124, v120
	v_mul_f32_e32 v131, 0xbfb8aa3b, v126
	v_exp_f32_e32 v131, v131
	v_mul_f32_e32 v124, v125, v136
	v_add_f32_e32 v130, 1.0, v131
	v_rcp_f32_e32 v132, v130
	v_mul_f32_e32 v121, v124, v121
	v_mul_f32_e32 v125, 0xbfb8aa3b, v127
	v_cvt_pk_bf16_f32 v120, v120, v121
	v_exp_f32_e32 v125, v125
	s_nop 0
	v_add_f32_e32 v125, 1.0, v125
	v_rcp_f32_e32 v133, v125
	v_mul_f32_e32 v121, v126, v132
	v_mul_f32_e32 v121, v121, v122
	v_mul_f32_e32 v126, 0xbfb8aa3b, v116
	v_exp_f32_e32 v126, v126
	v_mul_f32_e32 v122, v127, v133
	v_add_f32_e32 v124, 1.0, v126
	v_rcp_f32_e32 v126, v124
	v_mul_f32_e32 v122, v122, v123
	v_cvt_pk_bf16_f32 v121, v121, v122
	v_mul_f32_e32 v122, 0xbfb8aa3b, v117
	v_exp_f32_e32 v122, v122
	global_store_dwordx2 v[128:129], v[120:121], off
	v_add_f32_e32 v122, 1.0, v122
	v_rcp_f32_e32 v125, v122
	v_mul_f32_e32 v120, v116, v126
	v_mov_b32_e32 v116, v120
	v_mul_f32_e32 v112, v116, v112
	v_mul_f32_e32 v121, 0xbfb8aa3b, v118
	v_exp_f32_e32 v121, v121
	v_mul_f32_e32 v116, v117, v125
	v_add_f32_e32 v120, 1.0, v121
	v_rcp_f32_e32 v123, v120
	v_mul_f32_e32 v113, v116, v113
	v_mul_f32_e32 v117, 0xbfb8aa3b, v119
	v_cvt_pk_bf16_f32 v112, v112, v113
	v_exp_f32_e32 v117, v117
	s_nop 0
	v_add_f32_e32 v117, 1.0, v117
	v_rcp_f32_e32 v122, v117
	v_mul_f32_e32 v113, v118, v123
	v_mul_f32_e32 v113, v113, v114
	v_mul_f32_e32 v118, 0xbfb8aa3b, v108
	v_exp_f32_e32 v118, v118
	v_mul_f32_e32 v114, v119, v122
	v_mul_f32_e32 v114, v114, v115
	v_add_f32_e32 v115, 1.0, v118
	v_rcp_f32_e32 v117, v115
	v_cvt_pk_bf16_f32 v113, v113, v114
	v_mul_f32_e32 v119, 0xbfb8aa3b, v109
	v_exp_f32_e32 v119, v119
	s_nop 0
	v_add_f32_e32 v116, 1.0, v119
	v_rcp_f32_e32 v120, v116
	v_mul_f32_e32 v114, v108, v117
	v_mov_b32_e32 v108, v114
	v_mul_f32_e32 v104, v108, v104
	v_mul_f32_e32 v115, 0xbfb8aa3b, v110
	v_exp_f32_e32 v115, v115
	v_mul_f32_e32 v108, v109, v120
	v_add_f32_e32 v114, 1.0, v115
	v_rcp_f32_e32 v117, v114
	v_mul_f32_e32 v105, v108, v105
	v_mul_f32_e32 v109, 0xbfb8aa3b, v111
	global_store_dwordx2 v[128:129], v[112:113], off offset:32
	v_cvt_pk_bf16_f32 v104, v104, v105
	v_exp_f32_e32 v109, v109
	s_nop 0
	v_add_f32_e32 v109, 1.0, v109
	v_rcp_f32_e32 v116, v109
	v_mul_f32_e32 v105, v110, v117
	v_mul_f32_e32 v105, v105, v106
	v_mul_f32_e32 v106, v111, v116
	v_mul_f32_e32 v108, 0xbfb8aa3b, v100
	v_exp_f32_e32 v108, v108
	v_mul_f32_e32 v106, v106, v107
	v_cvt_pk_bf16_f32 v105, v105, v106
	v_add_f32_e32 v108, 1.0, v108
	v_rcp_f32_e32 v110, v108
	v_add_co_u32_e32 v106, vcc, s73, v128
	v_lshl_add_u64 v[112:113], v[128:129], 0, s[30:31]
	s_nop 0
	v_addc_co_u32_e32 v107, vcc, 0, v129, vcc
	global_store_dwordx2 v[106:107], v[104:105], off
	v_mul_f32_e32 v106, 0xbfb8aa3b, v101
	v_exp_f32_e32 v106, v106
	s_nop 0
	v_add_f32_e32 v106, 1.0, v106
	v_rcp_f32_e32 v109, v106
	v_mul_f32_e32 v104, v100, v110
	v_mov_b32_e32 v100, v104
	v_mul_f32_e32 v96, v100, v96
	v_mul_f32_e32 v105, 0xbfb8aa3b, v102
	v_exp_f32_e32 v105, v105
	v_mul_f32_e32 v100, v101, v109
	v_add_f32_e32 v104, 1.0, v105
	v_rcp_f32_e32 v107, v104
	v_mul_f32_e32 v97, v100, v97
	v_mul_f32_e32 v101, 0xbfb8aa3b, v103
	v_cvt_pk_bf16_f32 v96, v96, v97
	v_exp_f32_e32 v101, v101
	s_nop 0
	v_add_f32_e32 v101, 1.0, v101
	v_rcp_f32_e32 v106, v101
	v_mul_f32_e32 v97, v102, v107
	v_mul_f32_e32 v97, v97, v98
	v_mul_f32_e32 v102, 0xbfb8aa3b, v92
	v_exp_f32_e32 v102, v102
	v_mul_f32_e32 v98, v103, v106
	v_mul_f32_e32 v98, v98, v99
	v_add_f32_e32 v99, 1.0, v102
	v_rcp_f32_e32 v101, v99
	v_cvt_pk_bf16_f32 v97, v97, v98
	v_mul_f32_e32 v103, 0xbfb8aa3b, v93
	v_exp_f32_e32 v103, v103
	s_nop 0
	v_add_f32_e32 v100, 1.0, v103
	v_rcp_f32_e32 v104, v100
	v_mul_f32_e32 v98, v92, v101
	v_mov_b32_e32 v92, v98
	v_mul_f32_e32 v88, v92, v88
	v_mul_f32_e32 v99, 0xbfb8aa3b, v94
	v_exp_f32_e32 v99, v99
	v_mul_f32_e32 v92, v93, v104
	v_add_f32_e32 v98, 1.0, v99
	v_rcp_f32_e32 v101, v98
	v_mul_f32_e32 v89, v92, v89
	v_mul_f32_e32 v93, 0xbfb8aa3b, v95
	global_store_dwordx2 v[112:113], v[96:97], off offset:32
	v_cvt_pk_bf16_f32 v88, v88, v89
	v_exp_f32_e32 v93, v93
	s_nop 0
	v_add_f32_e32 v93, 1.0, v93
	v_rcp_f32_e32 v100, v93
	v_mul_f32_e32 v89, v94, v101
	v_mul_f32_e32 v89, v89, v90
	v_mul_f32_e32 v90, v95, v100
	v_mul_f32_e32 v92, 0xbfb8aa3b, v84
	v_exp_f32_e32 v92, v92
	v_mul_f32_e32 v90, v90, v91
	v_cvt_pk_bf16_f32 v89, v89, v90
	v_add_f32_e32 v92, 1.0, v92
	v_rcp_f32_e32 v94, v92
	v_add_co_u32_e32 v90, vcc, s69, v128
	v_lshl_add_u64 v[96:97], v[128:129], 0, s[34:35]
	s_nop 0
	v_addc_co_u32_e32 v91, vcc, 0, v129, vcc
	global_store_dwordx2 v[90:91], v[88:89], off
	v_mul_f32_e32 v90, 0xbfb8aa3b, v85
	v_exp_f32_e32 v90, v90
	s_nop 0
	v_add_f32_e32 v90, 1.0, v90
	v_rcp_f32_e32 v93, v90
	v_mul_f32_e32 v88, v84, v94
	v_mov_b32_e32 v84, v88
	v_mul_f32_e32 v80, v84, v80
	v_mul_f32_e32 v89, 0xbfb8aa3b, v86
	v_exp_f32_e32 v89, v89
	v_mul_f32_e32 v84, v85, v93
	v_add_f32_e32 v88, 1.0, v89
	v_rcp_f32_e32 v91, v88
	v_mul_f32_e32 v81, v84, v81
	v_mul_f32_e32 v85, 0xbfb8aa3b, v87
	v_cvt_pk_bf16_f32 v80, v80, v81
	v_exp_f32_e32 v85, v85
	s_nop 0
	v_add_f32_e32 v85, 1.0, v85
	v_rcp_f32_e32 v90, v85
	v_mul_f32_e32 v81, v86, v91
	v_mul_f32_e32 v81, v81, v82
	v_mul_f32_e32 v86, 0xbfb8aa3b, v76
	v_exp_f32_e32 v86, v86
	v_mul_f32_e32 v82, v87, v90
	v_mul_f32_e32 v82, v82, v83
	v_add_f32_e32 v83, 1.0, v86
	v_rcp_f32_e32 v85, v83
	v_cvt_pk_bf16_f32 v81, v81, v82
	v_mul_f32_e32 v87, 0xbfb8aa3b, v77
	v_exp_f32_e32 v87, v87
	s_nop 0
	v_add_f32_e32 v84, 1.0, v87
	v_rcp_f32_e32 v88, v84
	v_mul_f32_e32 v82, v76, v85
	v_mov_b32_e32 v76, v82
	v_mul_f32_e32 v72, v76, v72
	v_mul_f32_e32 v83, 0xbfb8aa3b, v78
	v_exp_f32_e32 v83, v83
	v_mul_f32_e32 v76, v77, v88
	v_add_f32_e32 v82, 1.0, v83
	v_rcp_f32_e32 v85, v82
	v_mul_f32_e32 v73, v76, v73
	v_mul_f32_e32 v77, 0xbfb8aa3b, v79
	global_store_dwordx2 v[96:97], v[80:81], off offset:32
	v_cvt_pk_bf16_f32 v72, v72, v73
	v_exp_f32_e32 v77, v77
	s_nop 0
	v_add_f32_e32 v77, 1.0, v77
	v_rcp_f32_e32 v84, v77
	v_mul_f32_e32 v73, v78, v85
	v_mul_f32_e32 v73, v73, v74
	v_mul_f32_e32 v74, v79, v84
	v_mul_f32_e32 v76, 0xbfb8aa3b, v68
	v_exp_f32_e32 v76, v76
	v_mul_f32_e32 v74, v74, v75
	v_cvt_pk_bf16_f32 v73, v73, v74
	v_add_f32_e32 v76, 1.0, v76
	v_rcp_f32_e32 v78, v76
	v_add_co_u32_e32 v74, vcc, s72, v128
	v_lshl_add_u64 v[80:81], v[128:129], 0, s[36:37]
	s_nop 0
	v_addc_co_u32_e32 v75, vcc, 0, v129, vcc
	global_store_dwordx2 v[74:75], v[72:73], off
	v_mul_f32_e32 v74, 0xbfb8aa3b, v69
	v_exp_f32_e32 v74, v74
	s_nop 0
	v_add_f32_e32 v74, 1.0, v74
	v_rcp_f32_e32 v77, v74
	v_mul_f32_e32 v72, v68, v78
	v_mov_b32_e32 v68, v72
	v_mul_f32_e32 v64, v68, v64
	v_mul_f32_e32 v73, 0xbfb8aa3b, v70
	v_exp_f32_e32 v73, v73
	v_mul_f32_e32 v68, v69, v77
	v_add_f32_e32 v72, 1.0, v73
	v_rcp_f32_e32 v75, v72
	v_mul_f32_e32 v65, v68, v65
	v_mul_f32_e32 v69, 0xbfb8aa3b, v71
	v_cvt_pk_bf16_f32 v64, v64, v65
	v_exp_f32_e32 v69, v69
	s_nop 0
	v_add_f32_e32 v69, 1.0, v69
	v_rcp_f32_e32 v74, v69
	v_mul_f32_e32 v65, v70, v75
	v_mul_f32_e32 v65, v65, v66
	v_mul_f32_e32 v70, 0xbfb8aa3b, v60
	v_exp_f32_e32 v70, v70
	v_mul_f32_e32 v66, v71, v74
	v_mul_f32_e32 v66, v66, v67
	v_add_f32_e32 v67, 1.0, v70
	v_rcp_f32_e32 v69, v67
	v_cvt_pk_bf16_f32 v65, v65, v66
	v_mul_f32_e32 v71, 0xbfb8aa3b, v61
	v_exp_f32_e32 v71, v71
	s_nop 0
	v_add_f32_e32 v68, 1.0, v71
	v_rcp_f32_e32 v72, v68
	v_mul_f32_e32 v66, v60, v69
	v_mov_b32_e32 v60, v66
	v_mul_f32_e32 v56, v60, v56
	v_mul_f32_e32 v67, 0xbfb8aa3b, v62
	v_exp_f32_e32 v67, v67
	v_mul_f32_e32 v60, v61, v72
	v_add_f32_e32 v66, 1.0, v67
	v_rcp_f32_e32 v69, v66
	v_mul_f32_e32 v57, v60, v57
	v_mul_f32_e32 v61, 0xbfb8aa3b, v63
	global_store_dwordx2 v[80:81], v[64:65], off offset:32
	v_cvt_pk_bf16_f32 v56, v56, v57
	v_exp_f32_e32 v61, v61
	s_nop 0
	v_add_f32_e32 v61, 1.0, v61
	v_rcp_f32_e32 v68, v61
	v_mul_f32_e32 v57, v62, v69
	v_mul_f32_e32 v57, v57, v58
	v_mul_f32_e32 v58, v63, v68
	v_mul_f32_e32 v60, 0xbfb8aa3b, v52
	v_exp_f32_e32 v60, v60
	v_mul_f32_e32 v58, v58, v59
	v_cvt_pk_bf16_f32 v57, v57, v58
	v_add_f32_e32 v60, 1.0, v60
	v_rcp_f32_e32 v62, v60
	v_add_co_u32_e32 v58, vcc, s78, v128
	v_lshl_add_u64 v[64:65], v[128:129], 0, s[42:43]
	s_nop 0
	v_addc_co_u32_e32 v59, vcc, 0, v129, vcc
	global_store_dwordx2 v[58:59], v[56:57], off
	v_mul_f32_e32 v58, 0xbfb8aa3b, v53
	v_exp_f32_e32 v58, v58
	s_nop 0
	v_add_f32_e32 v58, 1.0, v58
	v_rcp_f32_e32 v61, v58
	v_mul_f32_e32 v56, v52, v62
	v_mov_b32_e32 v52, v56
	v_mul_f32_e32 v48, v52, v48
	v_mul_f32_e32 v57, 0xbfb8aa3b, v54
	v_exp_f32_e32 v57, v57
	v_mul_f32_e32 v52, v53, v61
	v_add_f32_e32 v56, 1.0, v57
	v_rcp_f32_e32 v59, v56
	v_mul_f32_e32 v49, v52, v49
	v_mul_f32_e32 v53, 0xbfb8aa3b, v55
	v_cvt_pk_bf16_f32 v48, v48, v49
	v_exp_f32_e32 v53, v53
	s_nop 0
	v_add_f32_e32 v53, 1.0, v53
	v_rcp_f32_e32 v58, v53
	v_mul_f32_e32 v49, v54, v59
	v_mul_f32_e32 v49, v49, v50
	v_mul_f32_e32 v54, 0xbfb8aa3b, v44
	v_exp_f32_e32 v54, v54
	v_mul_f32_e32 v50, v55, v58
	v_mul_f32_e32 v50, v50, v51
	v_add_f32_e32 v51, 1.0, v54
	v_rcp_f32_e32 v53, v51
	v_cvt_pk_bf16_f32 v49, v49, v50
	v_mul_f32_e32 v55, 0xbfb8aa3b, v45
	v_exp_f32_e32 v55, v55
	s_nop 0
	v_add_f32_e32 v52, 1.0, v55
	v_rcp_f32_e32 v56, v52
	v_mul_f32_e32 v50, v44, v53
	v_mov_b32_e32 v44, v50
	v_mul_f32_e32 v40, v44, v40
	v_mul_f32_e32 v51, 0xbfb8aa3b, v46
	v_exp_f32_e32 v51, v51
	v_mul_f32_e32 v44, v45, v56
	v_add_f32_e32 v50, 1.0, v51
	v_rcp_f32_e32 v53, v50
	v_mul_f32_e32 v41, v44, v41
	v_mul_f32_e32 v45, 0xbfb8aa3b, v47
	global_store_dwordx2 v[64:65], v[48:49], off offset:32
	v_cvt_pk_bf16_f32 v40, v40, v41
	v_exp_f32_e32 v45, v45
	s_nop 0
	v_add_f32_e32 v45, 1.0, v45
	v_rcp_f32_e32 v52, v45
	v_mul_f32_e32 v41, v46, v53
	v_mul_f32_e32 v41, v41, v42
	v_mul_f32_e32 v42, v47, v52
	v_mul_f32_e32 v44, 0xbfb8aa3b, v36
	v_exp_f32_e32 v44, v44
	v_mul_f32_e32 v42, v42, v43
	v_cvt_pk_bf16_f32 v41, v41, v42
	v_add_f32_e32 v44, 1.0, v44
	v_rcp_f32_e32 v46, v44
	v_add_co_u32_e32 v42, vcc, s79, v128
	v_lshl_add_u64 v[48:49], v[128:129], 0, s[44:45]
	s_nop 0
	v_addc_co_u32_e32 v43, vcc, 0, v129, vcc
	global_store_dwordx2 v[42:43], v[40:41], off
	v_mul_f32_e32 v42, 0xbfb8aa3b, v37
	v_exp_f32_e32 v42, v42
	s_nop 0
	v_add_f32_e32 v42, 1.0, v42
	v_rcp_f32_e32 v45, v42
	v_mul_f32_e32 v40, v36, v46
	v_mov_b32_e32 v36, v40
	v_mul_f32_e32 v32, v36, v32
	v_mul_f32_e32 v41, 0xbfb8aa3b, v38
	v_exp_f32_e32 v41, v41
	v_mul_f32_e32 v36, v37, v45
	v_add_f32_e32 v40, 1.0, v41
	v_rcp_f32_e32 v43, v40
	v_mul_f32_e32 v33, v36, v33
	v_mul_f32_e32 v37, 0xbfb8aa3b, v39
	v_cvt_pk_bf16_f32 v32, v32, v33
	v_exp_f32_e32 v37, v37
	s_nop 0
	v_add_f32_e32 v37, 1.0, v37
	v_rcp_f32_e32 v42, v37
	v_mul_f32_e32 v33, v38, v43
	v_mul_f32_e32 v33, v33, v34
	v_mul_f32_e32 v38, 0xbfb8aa3b, v28
	v_exp_f32_e32 v38, v38
	v_mul_f32_e32 v34, v39, v42
	v_mul_f32_e32 v34, v34, v35
	v_add_f32_e32 v35, 1.0, v38
	v_rcp_f32_e32 v37, v35
	v_cvt_pk_bf16_f32 v33, v33, v34
	v_mul_f32_e32 v39, 0xbfb8aa3b, v29
	v_exp_f32_e32 v39, v39
	s_nop 0
	v_add_f32_e32 v36, 1.0, v39
	v_rcp_f32_e32 v40, v36
	v_mul_f32_e32 v34, v28, v37
	v_mov_b32_e32 v28, v34
	v_mul_f32_e32 v24, v28, v24
	v_mul_f32_e32 v35, 0xbfb8aa3b, v30
	v_exp_f32_e32 v35, v35
	v_mul_f32_e32 v28, v29, v40
	v_add_f32_e32 v34, 1.0, v35
	v_rcp_f32_e32 v37, v34
	v_mul_f32_e32 v25, v28, v25
	v_mul_f32_e32 v29, 0xbfb8aa3b, v31
	global_store_dwordx2 v[48:49], v[32:33], off offset:32
	v_cvt_pk_bf16_f32 v24, v24, v25
	v_exp_f32_e32 v29, v29
	s_nop 0
	v_add_f32_e32 v29, 1.0, v29
	v_rcp_f32_e32 v36, v29
	v_mul_f32_e32 v25, v30, v37
	v_mul_f32_e32 v25, v25, v26
	v_mul_f32_e32 v26, v31, v36
	v_mul_f32_e32 v28, 0xbfb8aa3b, v20
	v_exp_f32_e32 v28, v28
	v_mul_f32_e32 v26, v26, v27
	v_cvt_pk_bf16_f32 v25, v25, v26
	v_add_f32_e32 v28, 1.0, v28
	v_rcp_f32_e32 v30, v28
	v_add_co_u32_e32 v26, vcc, s80, v128
	v_lshl_add_u64 v[32:33], v[128:129], 0, s[46:47]
	s_nop 0
	v_addc_co_u32_e32 v27, vcc, 0, v129, vcc
	global_store_dwordx2 v[26:27], v[24:25], off
	v_mul_f32_e32 v26, 0xbfb8aa3b, v21
	v_exp_f32_e32 v26, v26
	s_nop 0
	v_add_f32_e32 v26, 1.0, v26
	v_rcp_f32_e32 v29, v26
	v_mul_f32_e32 v24, v20, v30
	v_mov_b32_e32 v20, v24
	v_mul_f32_e32 v16, v20, v16
	v_mul_f32_e32 v25, 0xbfb8aa3b, v22
	v_exp_f32_e32 v25, v25
	v_mul_f32_e32 v20, v21, v29
	v_add_f32_e32 v24, 1.0, v25
	v_rcp_f32_e32 v27, v24
	v_mul_f32_e32 v17, v20, v17
	v_mul_f32_e32 v21, 0xbfb8aa3b, v23
	v_cvt_pk_bf16_f32 v16, v16, v17
	v_exp_f32_e32 v21, v21
	s_nop 0
	v_add_f32_e32 v21, 1.0, v21
	v_rcp_f32_e32 v26, v21
	v_mul_f32_e32 v17, v22, v27
	v_mul_f32_e32 v17, v17, v18
	v_mul_f32_e32 v22, 0xbfb8aa3b, v12
	v_exp_f32_e32 v22, v22
	v_mul_f32_e32 v18, v23, v26
	v_mul_f32_e32 v18, v18, v19
	v_add_f32_e32 v19, 1.0, v22
	v_rcp_f32_e32 v21, v19
	v_cvt_pk_bf16_f32 v17, v17, v18
	v_mul_f32_e32 v23, 0xbfb8aa3b, v13
	v_exp_f32_e32 v23, v23
	s_nop 0
	v_add_f32_e32 v20, 1.0, v23
	v_rcp_f32_e32 v24, v20
	v_mul_f32_e32 v18, v12, v21
	v_mov_b32_e32 v12, v18
	v_mul_f32_e32 v8, v12, v8
	v_mul_f32_e32 v19, 0xbfb8aa3b, v14
	v_exp_f32_e32 v19, v19
	v_mul_f32_e32 v12, v13, v24
	v_add_f32_e32 v18, 1.0, v19
	v_rcp_f32_e32 v21, v18
	v_mul_f32_e32 v9, v12, v9
	v_mul_f32_e32 v13, 0xbfb8aa3b, v15
	global_store_dwordx2 v[32:33], v[16:17], off offset:32
	v_cvt_pk_bf16_f32 v8, v8, v9
	v_exp_f32_e32 v13, v13
	s_nop 0
	v_add_f32_e32 v13, 1.0, v13
	v_rcp_f32_e32 v20, v13
	v_mul_f32_e32 v9, v14, v21
	v_mul_f32_e32 v9, v9, v10
	v_mul_f32_e32 v10, v15, v20
	v_mul_f32_e32 v12, 0xbfb8aa3b, v4
	v_exp_f32_e32 v12, v12
	v_mul_f32_e32 v10, v10, v11
	v_cvt_pk_bf16_f32 v9, v9, v10
	v_add_f32_e32 v12, 1.0, v12
	v_rcp_f32_e32 v14, v12
	v_add_co_u32_e32 v10, vcc, s81, v128
	v_lshl_add_u64 v[16:17], v[128:129], 0, s[48:49]
	s_nop 0
	v_addc_co_u32_e32 v11, vcc, 0, v129, vcc
	global_store_dwordx2 v[10:11], v[8:9], off
	v_mul_f32_e32 v10, 0xbfb8aa3b, v5
	v_exp_f32_e32 v10, v10
	s_nop 0
	v_add_f32_e32 v10, 1.0, v10
	v_rcp_f32_e32 v13, v10
	v_mul_f32_e32 v8, v4, v14
	v_mov_b32_e32 v4, v8
	v_mul_f32_e32 v0, v4, v0
	v_mul_f32_e32 v9, 0xbfb8aa3b, v6
	v_exp_f32_e32 v9, v9
	v_mul_f32_e32 v4, v5, v13
	v_add_f32_e32 v8, 1.0, v9
	v_rcp_f32_e32 v11, v8
	v_mul_f32_e32 v1, v4, v1
	v_mul_f32_e32 v5, 0xbfb8aa3b, v7
	v_cvt_pk_bf16_f32 v0, v0, v1
	v_exp_f32_e32 v5, v5
	s_nop 0
	v_add_f32_e32 v5, 1.0, v5
	v_rcp_f32_e32 v10, v5
	v_mul_f32_e32 v1, v6, v11
	v_mul_f32_e32 v1, v1, v2
	v_mul_f32_e32 v2, v7, v10
	v_mul_f32_e32 v2, v2, v3
	v_cvt_pk_bf16_f32 v1, v1, v2
	global_store_dwordx2 v[16:17], v[0:1], off offset:32
	s_and_b64 vcc, exec, s[4:5]
	v_mov_b32_e32 v4, v180
	s_mov_b32 s82, s50
	v_mov_b32_e32 v198, v192
	v_mov_b64_e32 v[2:3], v[196:197]
	v_mov_b64_e32 v[0:1], v[194:195]
	s_mov_b32 s90, s91
	s_cbranch_vccnz .LBB0_1752

.Lts_a_e0:
	v_mul_f32_e32 v129, 0xbfb8aa3b, v124
	v_exp_f32_e32 v132, v129
	s_ashr_i32 s6, s82, 1
	v_add_u32_e32 v130, s6, v212
	v_add_u32_e32 v128, v198, v210
	v_add_f32_e32 v132, 1.0, v132
	v_rcp_f32_e32 v134, v132
	v_ashrrev_i32_e32 v129, 31, v128
	v_lshlrev_b64 v[128:129], 11, v[128:129]
	v_ashrrev_i32_e32 v131, 31, v130
	v_lshl_add_u64 v[128:129], s[14:15], 0, v[128:129]
	v_lshl_add_u64 v[128:129], v[130:131], 1, v[128:129]
	v_mul_f32_e32 v135, 0xbfb8aa3b, v125
	v_exp_f32_e32 v135, v135
	s_nop 0
	v_add_f32_e32 v133, 1.0, v135
	v_rcp_f32_e32 v136, v133
	v_mul_f32_e32 v130, v124, v134
	v_mov_b32_e32 v124, v130
	v_mul_f32_e32 v120, v124, v120
	v_mul_f32_e32 v131, 0xbfb8aa3b, v126
	v_exp_f32_e32 v131, v131
	v_mul_f32_e32 v124, v125, v136
	v_add_f32_e32 v130, 1.0, v131
	v_rcp_f32_e32 v132, v130
	v_mul_f32_e32 v121, v124, v121
	v_mul_f32_e32 v125, 0xbfb8aa3b, v127
	v_cvt_pk_bf16_f32 v120, v120, v121
	v_exp_f32_e32 v125, v125
	s_nop 0
	v_add_f32_e32 v125, 1.0, v125
	v_rcp_f32_e32 v133, v125
	v_mul_f32_e32 v121, v126, v132
	v_mul_f32_e32 v121, v121, v122
	v_mul_f32_e32 v126, 0xbfb8aa3b, v116
	v_exp_f32_e32 v126, v126
	v_mul_f32_e32 v122, v127, v133
	v_add_f32_e32 v124, 1.0, v126
	v_rcp_f32_e32 v126, v124
	v_mul_f32_e32 v122, v122, v123
	v_cvt_pk_bf16_f32 v121, v121, v122
	v_mul_f32_e32 v122, 0xbfb8aa3b, v117
	v_exp_f32_e32 v122, v122
	global_store_dwordx2 v[128:129], v[120:121], off
	v_add_f32_e32 v122, 1.0, v122
	v_rcp_f32_e32 v125, v122
	v_mul_f32_e32 v120, v116, v126
	v_mov_b32_e32 v116, v120
	v_mul_f32_e32 v112, v116, v112
	v_mul_f32_e32 v121, 0xbfb8aa3b, v118
	v_exp_f32_e32 v121, v121
	v_mul_f32_e32 v116, v117, v125
	v_add_f32_e32 v120, 1.0, v121
	v_rcp_f32_e32 v123, v120
	v_mul_f32_e32 v113, v116, v113
	v_mul_f32_e32 v117, 0xbfb8aa3b, v119
	v_cvt_pk_bf16_f32 v112, v112, v113
	v_exp_f32_e32 v117, v117
	s_nop 0
	v_add_f32_e32 v117, 1.0, v117
	v_rcp_f32_e32 v122, v117
	v_mul_f32_e32 v113, v118, v123
	v_mul_f32_e32 v113, v113, v114
	v_mul_f32_e32 v118, 0xbfb8aa3b, v108
	v_exp_f32_e32 v118, v118
	v_mul_f32_e32 v114, v119, v122
	v_mul_f32_e32 v114, v114, v115
	v_add_f32_e32 v115, 1.0, v118
	v_rcp_f32_e32 v117, v115
	v_cvt_pk_bf16_f32 v113, v113, v114
	v_mul_f32_e32 v119, 0xbfb8aa3b, v109
	v_exp_f32_e32 v119, v119
	s_nop 0
	v_add_f32_e32 v116, 1.0, v119
	v_rcp_f32_e32 v120, v116
	v_mul_f32_e32 v114, v108, v117
	v_mov_b32_e32 v108, v114
	v_mul_f32_e32 v104, v108, v104
	v_mul_f32_e32 v115, 0xbfb8aa3b, v110
	v_exp_f32_e32 v115, v115
	v_mul_f32_e32 v108, v109, v120
	v_add_f32_e32 v114, 1.0, v115
	v_rcp_f32_e32 v117, v114
	v_mul_f32_e32 v105, v108, v105
	v_mul_f32_e32 v109, 0xbfb8aa3b, v111
	global_store_dwordx2 v[128:129], v[112:113], off offset:32
	v_cvt_pk_bf16_f32 v104, v104, v105
	v_exp_f32_e32 v109, v109
	s_nop 0
	v_add_f32_e32 v109, 1.0, v109
	v_rcp_f32_e32 v116, v109
	v_mul_f32_e32 v105, v110, v117
	v_mul_f32_e32 v105, v105, v106
	v_mul_f32_e32 v106, v111, v116
	v_mul_f32_e32 v108, 0xbfb8aa3b, v100
	v_exp_f32_e32 v108, v108
	v_mul_f32_e32 v106, v106, v107
	v_cvt_pk_bf16_f32 v105, v105, v106
	v_add_f32_e32 v108, 1.0, v108
	v_rcp_f32_e32 v110, v108
	v_add_co_u32_e32 v106, vcc, s73, v128
	v_lshl_add_u64 v[112:113], v[128:129], 0, s[30:31]
	s_nop 0
	v_addc_co_u32_e32 v107, vcc, 0, v129, vcc
	global_store_dwordx2 v[106:107], v[104:105], off
	v_mul_f32_e32 v106, 0xbfb8aa3b, v101
	v_exp_f32_e32 v106, v106
	s_nop 0
	v_add_f32_e32 v106, 1.0, v106
	v_rcp_f32_e32 v109, v106
	v_mul_f32_e32 v104, v100, v110
	v_mov_b32_e32 v100, v104
	v_mul_f32_e32 v96, v100, v96
	v_mul_f32_e32 v105, 0xbfb8aa3b, v102
	v_exp_f32_e32 v105, v105
	v_mul_f32_e32 v100, v101, v109
	v_add_f32_e32 v104, 1.0, v105
	v_rcp_f32_e32 v107, v104
	v_mul_f32_e32 v97, v100, v97
	v_mul_f32_e32 v101, 0xbfb8aa3b, v103
	v_cvt_pk_bf16_f32 v96, v96, v97
	v_exp_f32_e32 v101, v101
	s_nop 0
	v_add_f32_e32 v101, 1.0, v101
	v_rcp_f32_e32 v106, v101
	v_mul_f32_e32 v97, v102, v107
	v_mul_f32_e32 v97, v97, v98
	v_mul_f32_e32 v102, 0xbfb8aa3b, v92
	v_exp_f32_e32 v102, v102
	v_mul_f32_e32 v98, v103, v106
	v_mul_f32_e32 v98, v98, v99
	v_add_f32_e32 v99, 1.0, v102
	v_rcp_f32_e32 v101, v99
	v_cvt_pk_bf16_f32 v97, v97, v98
	v_mul_f32_e32 v103, 0xbfb8aa3b, v93
	v_exp_f32_e32 v103, v103
	s_nop 0
	v_add_f32_e32 v100, 1.0, v103
	v_rcp_f32_e32 v104, v100
	v_mul_f32_e32 v98, v92, v101
	v_mov_b32_e32 v92, v98
	v_mul_f32_e32 v88, v92, v88
	v_mul_f32_e32 v99, 0xbfb8aa3b, v94
	v_exp_f32_e32 v99, v99
	v_mul_f32_e32 v92, v93, v104
	v_add_f32_e32 v98, 1.0, v99
	v_rcp_f32_e32 v101, v98
	v_mul_f32_e32 v89, v92, v89
	v_mul_f32_e32 v93, 0xbfb8aa3b, v95
	global_store_dwordx2 v[112:113], v[96:97], off offset:32
	v_cvt_pk_bf16_f32 v88, v88, v89
	v_exp_f32_e32 v93, v93
	s_nop 0
	v_add_f32_e32 v93, 1.0, v93
	v_rcp_f32_e32 v100, v93
	v_mul_f32_e32 v89, v94, v101
	v_mul_f32_e32 v89, v89, v90
	v_mul_f32_e32 v90, v95, v100
	v_mul_f32_e32 v92, 0xbfb8aa3b, v84
	v_exp_f32_e32 v92, v92
	v_mul_f32_e32 v90, v90, v91
	v_cvt_pk_bf16_f32 v89, v89, v90
	v_add_f32_e32 v92, 1.0, v92
	v_rcp_f32_e32 v94, v92
	v_add_co_u32_e32 v90, vcc, s69, v128
	v_lshl_add_u64 v[96:97], v[128:129], 0, s[34:35]
	s_nop 0
	v_addc_co_u32_e32 v91, vcc, 0, v129, vcc
	global_store_dwordx2 v[90:91], v[88:89], off
	v_mul_f32_e32 v90, 0xbfb8aa3b, v85
	v_exp_f32_e32 v90, v90
	s_nop 0
	v_add_f32_e32 v90, 1.0, v90
	v_rcp_f32_e32 v93, v90
	v_mul_f32_e32 v88, v84, v94
	v_mov_b32_e32 v84, v88
	v_mul_f32_e32 v80, v84, v80
	v_mul_f32_e32 v89, 0xbfb8aa3b, v86
	v_exp_f32_e32 v89, v89
	v_mul_f32_e32 v84, v85, v93
	v_add_f32_e32 v88, 1.0, v89
	v_rcp_f32_e32 v91, v88
	v_mul_f32_e32 v81, v84, v81
	v_mul_f32_e32 v85, 0xbfb8aa3b, v87
	v_cvt_pk_bf16_f32 v80, v80, v81
	v_exp_f32_e32 v85, v85
	s_nop 0
	v_add_f32_e32 v85, 1.0, v85
	v_rcp_f32_e32 v90, v85
	v_mul_f32_e32 v81, v86, v91
	v_mul_f32_e32 v81, v81, v82
	v_mul_f32_e32 v86, 0xbfb8aa3b, v76
	v_exp_f32_e32 v86, v86
	v_mul_f32_e32 v82, v87, v90
	v_mul_f32_e32 v82, v82, v83
	v_add_f32_e32 v83, 1.0, v86
	v_rcp_f32_e32 v85, v83
	v_cvt_pk_bf16_f32 v81, v81, v82
	v_mul_f32_e32 v87, 0xbfb8aa3b, v77
	v_exp_f32_e32 v87, v87
	s_nop 0
	v_add_f32_e32 v84, 1.0, v87
	v_rcp_f32_e32 v88, v84
	v_mul_f32_e32 v82, v76, v85
	v_mov_b32_e32 v76, v82
	v_mul_f32_e32 v72, v76, v72
	v_mul_f32_e32 v83, 0xbfb8aa3b, v78
	v_exp_f32_e32 v83, v83
	v_mul_f32_e32 v76, v77, v88
	v_add_f32_e32 v82, 1.0, v83
	v_rcp_f32_e32 v85, v82
	v_mul_f32_e32 v73, v76, v73
	v_mul_f32_e32 v77, 0xbfb8aa3b, v79
	global_store_dwordx2 v[96:97], v[80:81], off offset:32
	v_cvt_pk_bf16_f32 v72, v72, v73
	v_exp_f32_e32 v77, v77
	s_nop 0
	v_add_f32_e32 v77, 1.0, v77
	v_rcp_f32_e32 v84, v77
	v_mul_f32_e32 v73, v78, v85
	v_mul_f32_e32 v73, v73, v74
	v_mul_f32_e32 v74, v79, v84
	v_mul_f32_e32 v76, 0xbfb8aa3b, v68
	v_exp_f32_e32 v76, v76
	v_mul_f32_e32 v74, v74, v75
	v_cvt_pk_bf16_f32 v73, v73, v74
	v_add_f32_e32 v76, 1.0, v76
	v_rcp_f32_e32 v78, v76
	v_add_co_u32_e32 v74, vcc, s72, v128
	v_lshl_add_u64 v[80:81], v[128:129], 0, s[36:37]
	s_nop 0
	v_addc_co_u32_e32 v75, vcc, 0, v129, vcc
	global_store_dwordx2 v[74:75], v[72:73], off
	v_mul_f32_e32 v74, 0xbfb8aa3b, v69
	v_exp_f32_e32 v74, v74
	s_nop 0
	v_add_f32_e32 v74, 1.0, v74
	v_rcp_f32_e32 v77, v74
	v_mul_f32_e32 v72, v68, v78
	v_mov_b32_e32 v68, v72
	v_mul_f32_e32 v64, v68, v64
	v_mul_f32_e32 v73, 0xbfb8aa3b, v70
	v_exp_f32_e32 v73, v73
	v_mul_f32_e32 v68, v69, v77
	v_add_f32_e32 v72, 1.0, v73
	v_rcp_f32_e32 v75, v72
	v_mul_f32_e32 v65, v68, v65
	v_mul_f32_e32 v69, 0xbfb8aa3b, v71
	v_cvt_pk_bf16_f32 v64, v64, v65
	v_exp_f32_e32 v69, v69
	s_nop 0
	v_add_f32_e32 v69, 1.0, v69
	v_rcp_f32_e32 v74, v69
	v_mul_f32_e32 v65, v70, v75
	v_mul_f32_e32 v65, v65, v66
	v_mul_f32_e32 v70, 0xbfb8aa3b, v60
	v_exp_f32_e32 v70, v70
	v_mul_f32_e32 v66, v71, v74
	v_mul_f32_e32 v66, v66, v67
	v_add_f32_e32 v67, 1.0, v70
	v_rcp_f32_e32 v69, v67
	v_cvt_pk_bf16_f32 v65, v65, v66
	v_mul_f32_e32 v71, 0xbfb8aa3b, v61
	v_exp_f32_e32 v71, v71
	s_nop 0
	v_add_f32_e32 v68, 1.0, v71
	v_rcp_f32_e32 v72, v68
	v_mul_f32_e32 v66, v60, v69
	v_mov_b32_e32 v60, v66
	v_mul_f32_e32 v56, v60, v56
	v_mul_f32_e32 v67, 0xbfb8aa3b, v62
	v_exp_f32_e32 v67, v67
	v_mul_f32_e32 v60, v61, v72
	v_add_f32_e32 v66, 1.0, v67
	v_rcp_f32_e32 v69, v66
	v_mul_f32_e32 v57, v60, v57
	v_mul_f32_e32 v61, 0xbfb8aa3b, v63
	global_store_dwordx2 v[80:81], v[64:65], off offset:32
	v_cvt_pk_bf16_f32 v56, v56, v57
	v_exp_f32_e32 v61, v61
	s_nop 0
	v_add_f32_e32 v61, 1.0, v61
	v_rcp_f32_e32 v68, v61
	v_mul_f32_e32 v57, v62, v69
	v_mul_f32_e32 v57, v57, v58
	v_mul_f32_e32 v58, v63, v68
	v_mul_f32_e32 v60, 0xbfb8aa3b, v52
	v_exp_f32_e32 v60, v60
	v_mul_f32_e32 v58, v58, v59
	v_cvt_pk_bf16_f32 v57, v57, v58
	v_add_f32_e32 v60, 1.0, v60
	v_rcp_f32_e32 v62, v60
	v_add_co_u32_e32 v58, vcc, s78, v128
	v_lshl_add_u64 v[64:65], v[128:129], 0, s[42:43]
	s_nop 0
	v_addc_co_u32_e32 v59, vcc, 0, v129, vcc
	s_nop 0
	v_mul_f32_e32 v58, 0xbfb8aa3b, v53
	v_exp_f32_e32 v58, v58
	s_nop 0
	v_add_f32_e32 v58, 1.0, v58
	v_rcp_f32_e32 v61, v58
	v_mul_f32_e32 v56, v52, v62
	v_mov_b32_e32 v52, v56
	v_mul_f32_e32 v48, v52, v48
	v_mul_f32_e32 v57, 0xbfb8aa3b, v54
	v_exp_f32_e32 v57, v57
	v_mul_f32_e32 v52, v53, v61
	v_add_f32_e32 v56, 1.0, v57
	v_rcp_f32_e32 v59, v56
	v_mul_f32_e32 v49, v52, v49
	v_mul_f32_e32 v53, 0xbfb8aa3b, v55
	v_cvt_pk_bf16_f32 v48, v48, v49
	v_exp_f32_e32 v53, v53
	s_nop 0
	v_add_f32_e32 v53, 1.0, v53
	v_rcp_f32_e32 v58, v53
	v_mul_f32_e32 v49, v54, v59
	v_mul_f32_e32 v49, v49, v50
	v_mul_f32_e32 v54, 0xbfb8aa3b, v44
	v_exp_f32_e32 v54, v54
	v_mul_f32_e32 v50, v55, v58
	v_mul_f32_e32 v50, v50, v51
	v_add_f32_e32 v51, 1.0, v54
	v_rcp_f32_e32 v53, v51
	v_cvt_pk_bf16_f32 v49, v49, v50
	v_mul_f32_e32 v55, 0xbfb8aa3b, v45
	v_exp_f32_e32 v55, v55
	s_nop 0
	v_add_f32_e32 v52, 1.0, v55
	v_rcp_f32_e32 v56, v52
	v_mul_f32_e32 v50, v44, v53
	v_mov_b32_e32 v44, v50
	v_mul_f32_e32 v40, v44, v40
	v_mul_f32_e32 v51, 0xbfb8aa3b, v46
	v_exp_f32_e32 v51, v51
	v_mul_f32_e32 v44, v45, v56
	v_add_f32_e32 v50, 1.0, v51
	v_rcp_f32_e32 v53, v50
	v_mul_f32_e32 v41, v44, v41
	v_mul_f32_e32 v45, 0xbfb8aa3b, v47
	s_nop 0
	v_cvt_pk_bf16_f32 v40, v40, v41
	v_exp_f32_e32 v45, v45
	s_nop 0
	v_add_f32_e32 v45, 1.0, v45
	v_rcp_f32_e32 v52, v45
	v_mul_f32_e32 v41, v46, v53
	v_mul_f32_e32 v41, v41, v42
	v_mul_f32_e32 v42, v47, v52
	v_mul_f32_e32 v44, 0xbfb8aa3b, v36
	v_exp_f32_e32 v44, v44
	v_mul_f32_e32 v42, v42, v43
	v_cvt_pk_bf16_f32 v41, v41, v42
	v_add_f32_e32 v44, 1.0, v44
	v_rcp_f32_e32 v46, v44
	v_add_co_u32_e32 v42, vcc, s79, v128
	v_lshl_add_u64 v[48:49], v[128:129], 0, s[44:45]
	s_nop 0
	v_addc_co_u32_e32 v43, vcc, 0, v129, vcc
	s_nop 0
	v_mul_f32_e32 v42, 0xbfb8aa3b, v37
	v_exp_f32_e32 v42, v42
	s_nop 0
	v_add_f32_e32 v42, 1.0, v42
	v_rcp_f32_e32 v45, v42
	v_mul_f32_e32 v40, v36, v46
	v_mov_b32_e32 v36, v40
	v_mul_f32_e32 v32, v36, v32
	v_mul_f32_e32 v41, 0xbfb8aa3b, v38
	v_exp_f32_e32 v41, v41
	v_mul_f32_e32 v36, v37, v45
	v_add_f32_e32 v40, 1.0, v41
	v_rcp_f32_e32 v43, v40
	v_mul_f32_e32 v33, v36, v33
	v_mul_f32_e32 v37, 0xbfb8aa3b, v39
	v_cvt_pk_bf16_f32 v32, v32, v33
	v_exp_f32_e32 v37, v37
	s_nop 0
	v_add_f32_e32 v37, 1.0, v37
	v_rcp_f32_e32 v42, v37
	v_mul_f32_e32 v33, v38, v43
	v_mul_f32_e32 v33, v33, v34
	v_mul_f32_e32 v38, 0xbfb8aa3b, v28
	v_exp_f32_e32 v38, v38
	v_mul_f32_e32 v34, v39, v42
	v_mul_f32_e32 v34, v34, v35
	v_add_f32_e32 v35, 1.0, v38
	v_rcp_f32_e32 v37, v35
	v_cvt_pk_bf16_f32 v33, v33, v34
	v_mul_f32_e32 v39, 0xbfb8aa3b, v29
	v_exp_f32_e32 v39, v39
	s_nop 0
	v_add_f32_e32 v36, 1.0, v39
	v_rcp_f32_e32 v40, v36
	v_mul_f32_e32 v34, v28, v37
	v_mov_b32_e32 v28, v34
	v_mul_f32_e32 v24, v28, v24
	v_mul_f32_e32 v35, 0xbfb8aa3b, v30
	v_exp_f32_e32 v35, v35
	v_mul_f32_e32 v28, v29, v40
	v_add_f32_e32 v34, 1.0, v35
	v_rcp_f32_e32 v37, v34
	v_mul_f32_e32 v25, v28, v25
	v_mul_f32_e32 v29, 0xbfb8aa3b, v31
	s_nop 0
	v_cvt_pk_bf16_f32 v24, v24, v25
	v_exp_f32_e32 v29, v29
	s_nop 0
	v_add_f32_e32 v29, 1.0, v29
	v_rcp_f32_e32 v36, v29
	v_mul_f32_e32 v25, v30, v37
	v_mul_f32_e32 v25, v25, v26
	v_mul_f32_e32 v26, v31, v36
	v_mul_f32_e32 v28, 0xbfb8aa3b, v20
	v_exp_f32_e32 v28, v28
	v_mul_f32_e32 v26, v26, v27
	v_cvt_pk_bf16_f32 v25, v25, v26
	v_add_f32_e32 v28, 1.0, v28
	v_rcp_f32_e32 v30, v28
	v_add_co_u32_e32 v26, vcc, s80, v128
	v_lshl_add_u64 v[32:33], v[128:129], 0, s[46:47]
	s_nop 0
	v_addc_co_u32_e32 v27, vcc, 0, v129, vcc
	s_nop 0
	v_mul_f32_e32 v26, 0xbfb8aa3b, v21
	v_exp_f32_e32 v26, v26
	s_nop 0
	v_add_f32_e32 v26, 1.0, v26
	v_rcp_f32_e32 v29, v26
	v_mul_f32_e32 v24, v20, v30
	v_mov_b32_e32 v20, v24
	v_mul_f32_e32 v16, v20, v16
	v_mul_f32_e32 v25, 0xbfb8aa3b, v22
	v_exp_f32_e32 v25, v25
	v_mul_f32_e32 v20, v21, v29
	v_add_f32_e32 v24, 1.0, v25
	v_rcp_f32_e32 v27, v24
	v_mul_f32_e32 v17, v20, v17
	v_mul_f32_e32 v21, 0xbfb8aa3b, v23
	v_cvt_pk_bf16_f32 v16, v16, v17
	v_exp_f32_e32 v21, v21
	s_nop 0
	v_add_f32_e32 v21, 1.0, v21
	v_rcp_f32_e32 v26, v21
	v_mul_f32_e32 v17, v22, v27
	v_mul_f32_e32 v17, v17, v18
	v_mul_f32_e32 v22, 0xbfb8aa3b, v12
	v_exp_f32_e32 v22, v22
	v_mul_f32_e32 v18, v23, v26
	v_mul_f32_e32 v18, v18, v19
	v_add_f32_e32 v19, 1.0, v22
	v_rcp_f32_e32 v21, v19
	v_cvt_pk_bf16_f32 v17, v17, v18
	v_mul_f32_e32 v23, 0xbfb8aa3b, v13
	v_exp_f32_e32 v23, v23
	s_nop 0
	v_add_f32_e32 v20, 1.0, v23
	v_rcp_f32_e32 v24, v20
	v_mul_f32_e32 v18, v12, v21
	v_mov_b32_e32 v12, v18
	v_mul_f32_e32 v8, v12, v8
	v_mul_f32_e32 v19, 0xbfb8aa3b, v14
	v_exp_f32_e32 v19, v19
	v_mul_f32_e32 v12, v13, v24
	v_add_f32_e32 v18, 1.0, v19
	v_rcp_f32_e32 v21, v18
	v_mul_f32_e32 v9, v12, v9
	v_mul_f32_e32 v13, 0xbfb8aa3b, v15
	s_nop 0
	v_cvt_pk_bf16_f32 v8, v8, v9
	v_exp_f32_e32 v13, v13
	s_nop 0
	v_add_f32_e32 v13, 1.0, v13
	v_rcp_f32_e32 v20, v13
	v_mul_f32_e32 v9, v14, v21
	v_mul_f32_e32 v9, v9, v10
	v_mul_f32_e32 v10, v15, v20
	v_mul_f32_e32 v12, 0xbfb8aa3b, v4
	v_exp_f32_e32 v12, v12
	v_mul_f32_e32 v10, v10, v11
	v_cvt_pk_bf16_f32 v9, v9, v10
	v_add_f32_e32 v12, 1.0, v12
	v_rcp_f32_e32 v14, v12
	v_add_co_u32_e32 v10, vcc, s81, v128
	v_lshl_add_u64 v[16:17], v[128:129], 0, s[48:49]
	s_nop 0
	v_addc_co_u32_e32 v11, vcc, 0, v129, vcc
	s_nop 0
	v_mul_f32_e32 v10, 0xbfb8aa3b, v5
	v_exp_f32_e32 v10, v10
	s_nop 0
	v_add_f32_e32 v10, 1.0, v10
	v_rcp_f32_e32 v13, v10
	v_mul_f32_e32 v8, v4, v14
	v_mov_b32_e32 v4, v8
	v_mul_f32_e32 v0, v4, v0
	v_mul_f32_e32 v9, 0xbfb8aa3b, v6
	v_exp_f32_e32 v9, v9
	v_mul_f32_e32 v4, v5, v13
	v_add_f32_e32 v8, 1.0, v9
	v_rcp_f32_e32 v11, v8
	v_mul_f32_e32 v1, v4, v1
	v_mul_f32_e32 v5, 0xbfb8aa3b, v7
	v_cvt_pk_bf16_f32 v0, v0, v1
	v_exp_f32_e32 v5, v5
	s_nop 0
	v_add_f32_e32 v5, 1.0, v5
	v_rcp_f32_e32 v10, v5
	v_mul_f32_e32 v1, v6, v11
	v_mul_f32_e32 v1, v1, v2
	v_mul_f32_e32 v2, v7, v10
	v_mul_f32_e32 v2, v2, v3
	v_cvt_pk_bf16_f32 v1, v1, v2
	s_nop 0
	s_and_b64 vcc, exec, s[4:5]
	v_mov_b32_e32 v4, v180
	s_mov_b32 s82, s50
	v_mov_b32_e32 v198, v192
	v_mov_b64_e32 v[2:3], v[196:197]
	v_mov_b64_e32 v[0:1], v[194:195]
	s_branch .LBB0_1752

.Lts_a_e1:
	v_mul_f32_e32 v129, 0xbfb8aa3b, v124
	v_exp_f32_e32 v132, v129
	s_ashr_i32 s6, s82, 1
	v_add_u32_e32 v130, s6, v212
	v_add_u32_e32 v128, v198, v210
	v_add_f32_e32 v132, 1.0, v132
	v_rcp_f32_e32 v134, v132
	v_ashrrev_i32_e32 v129, 31, v128
	v_lshlrev_b64 v[128:129], 11, v[128:129]
	v_ashrrev_i32_e32 v131, 31, v130
	v_lshl_add_u64 v[128:129], s[14:15], 0, v[128:129]
	v_lshl_add_u64 v[128:129], v[130:131], 1, v[128:129]
	v_mul_f32_e32 v135, 0xbfb8aa3b, v125
	v_exp_f32_e32 v135, v135
	s_nop 0
	v_add_f32_e32 v133, 1.0, v135
	v_rcp_f32_e32 v136, v133
	v_mul_f32_e32 v130, v124, v134
	v_mov_b32_e32 v124, v130
	v_mul_f32_e32 v120, v124, v120
	v_mul_f32_e32 v131, 0xbfb8aa3b, v126
	v_exp_f32_e32 v131, v131
	v_mul_f32_e32 v124, v125, v136
	v_add_f32_e32 v130, 1.0, v131
	v_rcp_f32_e32 v132, v130
	v_mul_f32_e32 v121, v124, v121
	v_mul_f32_e32 v125, 0xbfb8aa3b, v127
	v_cvt_pk_bf16_f32 v120, v120, v121
	v_exp_f32_e32 v125, v125
	s_nop 0
	v_add_f32_e32 v125, 1.0, v125
	v_rcp_f32_e32 v133, v125
	v_mul_f32_e32 v121, v126, v132
	v_mul_f32_e32 v121, v121, v122
	v_mul_f32_e32 v126, 0xbfb8aa3b, v116
	v_exp_f32_e32 v126, v126
	v_mul_f32_e32 v122, v127, v133
	v_add_f32_e32 v124, 1.0, v126
	v_rcp_f32_e32 v126, v124
	v_mul_f32_e32 v122, v122, v123
	v_cvt_pk_bf16_f32 v121, v121, v122
	v_mul_f32_e32 v122, 0xbfb8aa3b, v117
	v_exp_f32_e32 v122, v122
	s_nop 0
	v_add_f32_e32 v122, 1.0, v122
	v_rcp_f32_e32 v125, v122
	v_mul_f32_e32 v120, v116, v126
	v_mov_b32_e32 v116, v120
	v_mul_f32_e32 v112, v116, v112
	v_mul_f32_e32 v121, 0xbfb8aa3b, v118
	v_exp_f32_e32 v121, v121
	v_mul_f32_e32 v116, v117, v125
	v_add_f32_e32 v120, 1.0, v121
	v_rcp_f32_e32 v123, v120
	v_mul_f32_e32 v113, v116, v113
	v_mul_f32_e32 v117, 0xbfb8aa3b, v119
	v_cvt_pk_bf16_f32 v112, v112, v113
	v_exp_f32_e32 v117, v117
	s_nop 0
	v_add_f32_e32 v117, 1.0, v117
	v_rcp_f32_e32 v122, v117
	v_mul_f32_e32 v113, v118, v123
	v_mul_f32_e32 v113, v113, v114
	v_mul_f32_e32 v118, 0xbfb8aa3b, v108
	v_exp_f32_e32 v118, v118
	v_mul_f32_e32 v114, v119, v122
	v_mul_f32_e32 v114, v114, v115
	v_add_f32_e32 v115, 1.0, v118
	v_rcp_f32_e32 v117, v115
	v_cvt_pk_bf16_f32 v113, v113, v114
	v_mul_f32_e32 v119, 0xbfb8aa3b, v109
	v_exp_f32_e32 v119, v119
	s_nop 0
	v_add_f32_e32 v116, 1.0, v119
	v_rcp_f32_e32 v120, v116
	v_mul_f32_e32 v114, v108, v117
	v_mov_b32_e32 v108, v114
	v_mul_f32_e32 v104, v108, v104
	v_mul_f32_e32 v115, 0xbfb8aa3b, v110
	v_exp_f32_e32 v115, v115
	v_mul_f32_e32 v108, v109, v120
	v_add_f32_e32 v114, 1.0, v115
	v_rcp_f32_e32 v117, v114
	v_mul_f32_e32 v105, v108, v105
	v_mul_f32_e32 v109, 0xbfb8aa3b, v111
	s_nop 0
	v_cvt_pk_bf16_f32 v104, v104, v105
	v_exp_f32_e32 v109, v109
	s_nop 0
	v_add_f32_e32 v109, 1.0, v109
	v_rcp_f32_e32 v116, v109
	v_mul_f32_e32 v105, v110, v117
	v_mul_f32_e32 v105, v105, v106
	v_mul_f32_e32 v106, v111, v116
	v_mul_f32_e32 v108, 0xbfb8aa3b, v100
	v_exp_f32_e32 v108, v108
	v_mul_f32_e32 v106, v106, v107
	v_cvt_pk_bf16_f32 v105, v105, v106
	v_add_f32_e32 v108, 1.0, v108
	v_rcp_f32_e32 v110, v108
	v_add_co_u32_e32 v106, vcc, s73, v128
	v_lshl_add_u64 v[112:113], v[128:129], 0, s[30:31]
	s_nop 0
	v_addc_co_u32_e32 v107, vcc, 0, v129, vcc
	s_nop 0
	v_mul_f32_e32 v106, 0xbfb8aa3b, v101
	v_exp_f32_e32 v106, v106
	s_nop 0
	v_add_f32_e32 v106, 1.0, v106
	v_rcp_f32_e32 v109, v106
	v_mul_f32_e32 v104, v100, v110
	v_mov_b32_e32 v100, v104
	v_mul_f32_e32 v96, v100, v96
	v_mul_f32_e32 v105, 0xbfb8aa3b, v102
	v_exp_f32_e32 v105, v105
	v_mul_f32_e32 v100, v101, v109
	v_add_f32_e32 v104, 1.0, v105
	v_rcp_f32_e32 v107, v104
	v_mul_f32_e32 v97, v100, v97
	v_mul_f32_e32 v101, 0xbfb8aa3b, v103
	v_cvt_pk_bf16_f32 v96, v96, v97
	v_exp_f32_e32 v101, v101
	s_nop 0
	v_add_f32_e32 v101, 1.0, v101
	v_rcp_f32_e32 v106, v101
	v_mul_f32_e32 v97, v102, v107
	v_mul_f32_e32 v97, v97, v98
	v_mul_f32_e32 v102, 0xbfb8aa3b, v92
	v_exp_f32_e32 v102, v102
	v_mul_f32_e32 v98, v103, v106
	v_mul_f32_e32 v98, v98, v99
	v_add_f32_e32 v99, 1.0, v102
	v_rcp_f32_e32 v101, v99
	v_cvt_pk_bf16_f32 v97, v97, v98
	v_mul_f32_e32 v103, 0xbfb8aa3b, v93
	v_exp_f32_e32 v103, v103
	s_nop 0
	v_add_f32_e32 v100, 1.0, v103
	v_rcp_f32_e32 v104, v100
	v_mul_f32_e32 v98, v92, v101
	v_mov_b32_e32 v92, v98
	v_mul_f32_e32 v88, v92, v88
	v_mul_f32_e32 v99, 0xbfb8aa3b, v94
	v_exp_f32_e32 v99, v99
	v_mul_f32_e32 v92, v93, v104
	v_add_f32_e32 v98, 1.0, v99
	v_rcp_f32_e32 v101, v98
	v_mul_f32_e32 v89, v92, v89
	v_mul_f32_e32 v93, 0xbfb8aa3b, v95
	s_nop 0
	v_cvt_pk_bf16_f32 v88, v88, v89
	v_exp_f32_e32 v93, v93
	s_nop 0
	v_add_f32_e32 v93, 1.0, v93
	v_rcp_f32_e32 v100, v93
	v_mul_f32_e32 v89, v94, v101
	v_mul_f32_e32 v89, v89, v90
	v_mul_f32_e32 v90, v95, v100
	v_mul_f32_e32 v92, 0xbfb8aa3b, v84
	v_exp_f32_e32 v92, v92
	v_mul_f32_e32 v90, v90, v91
	v_cvt_pk_bf16_f32 v89, v89, v90
	v_add_f32_e32 v92, 1.0, v92
	v_rcp_f32_e32 v94, v92
	v_add_co_u32_e32 v90, vcc, s69, v128
	v_lshl_add_u64 v[96:97], v[128:129], 0, s[34:35]
	s_nop 0
	v_addc_co_u32_e32 v91, vcc, 0, v129, vcc
	s_nop 0
	v_mul_f32_e32 v90, 0xbfb8aa3b, v85
	v_exp_f32_e32 v90, v90
	s_nop 0
	v_add_f32_e32 v90, 1.0, v90
	v_rcp_f32_e32 v93, v90
	v_mul_f32_e32 v88, v84, v94
	v_mov_b32_e32 v84, v88
	v_mul_f32_e32 v80, v84, v80
	v_mul_f32_e32 v89, 0xbfb8aa3b, v86
	v_exp_f32_e32 v89, v89
	v_mul_f32_e32 v84, v85, v93
	v_add_f32_e32 v88, 1.0, v89
	v_rcp_f32_e32 v91, v88
	v_mul_f32_e32 v81, v84, v81
	v_mul_f32_e32 v85, 0xbfb8aa3b, v87
	v_cvt_pk_bf16_f32 v80, v80, v81
	v_exp_f32_e32 v85, v85
	s_nop 0
	v_add_f32_e32 v85, 1.0, v85
	v_rcp_f32_e32 v90, v85
	v_mul_f32_e32 v81, v86, v91
	v_mul_f32_e32 v81, v81, v82
	v_mul_f32_e32 v86, 0xbfb8aa3b, v76
	v_exp_f32_e32 v86, v86
	v_mul_f32_e32 v82, v87, v90
	v_mul_f32_e32 v82, v82, v83
	v_add_f32_e32 v83, 1.0, v86
	v_rcp_f32_e32 v85, v83
	v_cvt_pk_bf16_f32 v81, v81, v82
	v_mul_f32_e32 v87, 0xbfb8aa3b, v77
	v_exp_f32_e32 v87, v87
	s_nop 0
	v_add_f32_e32 v84, 1.0, v87
	v_rcp_f32_e32 v88, v84
	v_mul_f32_e32 v82, v76, v85
	v_mov_b32_e32 v76, v82
	v_mul_f32_e32 v72, v76, v72
	v_mul_f32_e32 v83, 0xbfb8aa3b, v78
	v_exp_f32_e32 v83, v83
	v_mul_f32_e32 v76, v77, v88
	v_add_f32_e32 v82, 1.0, v83
	v_rcp_f32_e32 v85, v82
	v_mul_f32_e32 v73, v76, v73
	v_mul_f32_e32 v77, 0xbfb8aa3b, v79
	s_nop 0
	v_cvt_pk_bf16_f32 v72, v72, v73
	v_exp_f32_e32 v77, v77
	s_nop 0
	v_add_f32_e32 v77, 1.0, v77
	v_rcp_f32_e32 v84, v77
	v_mul_f32_e32 v73, v78, v85
	v_mul_f32_e32 v73, v73, v74
	v_mul_f32_e32 v74, v79, v84
	v_mul_f32_e32 v76, 0xbfb8aa3b, v68
	v_exp_f32_e32 v76, v76
	v_mul_f32_e32 v74, v74, v75
	v_cvt_pk_bf16_f32 v73, v73, v74
	v_add_f32_e32 v76, 1.0, v76
	v_rcp_f32_e32 v78, v76
	v_add_co_u32_e32 v74, vcc, s72, v128
	v_lshl_add_u64 v[80:81], v[128:129], 0, s[36:37]
	s_nop 0
	v_addc_co_u32_e32 v75, vcc, 0, v129, vcc
	s_nop 0
	v_mul_f32_e32 v74, 0xbfb8aa3b, v69
	v_exp_f32_e32 v74, v74
	s_nop 0
	v_add_f32_e32 v74, 1.0, v74
	v_rcp_f32_e32 v77, v74
	v_mul_f32_e32 v72, v68, v78
	v_mov_b32_e32 v68, v72
	v_mul_f32_e32 v64, v68, v64
	v_mul_f32_e32 v73, 0xbfb8aa3b, v70
	v_exp_f32_e32 v73, v73
	v_mul_f32_e32 v68, v69, v77
	v_add_f32_e32 v72, 1.0, v73
	v_rcp_f32_e32 v75, v72
	v_mul_f32_e32 v65, v68, v65
	v_mul_f32_e32 v69, 0xbfb8aa3b, v71
	v_cvt_pk_bf16_f32 v64, v64, v65
	v_exp_f32_e32 v69, v69
	s_nop 0
	v_add_f32_e32 v69, 1.0, v69
	v_rcp_f32_e32 v74, v69
	v_mul_f32_e32 v65, v70, v75
	v_mul_f32_e32 v65, v65, v66
	v_mul_f32_e32 v70, 0xbfb8aa3b, v60
	v_exp_f32_e32 v70, v70
	v_mul_f32_e32 v66, v71, v74
	v_mul_f32_e32 v66, v66, v67
	v_add_f32_e32 v67, 1.0, v70
	v_rcp_f32_e32 v69, v67
	v_cvt_pk_bf16_f32 v65, v65, v66
	v_mul_f32_e32 v71, 0xbfb8aa3b, v61
	v_exp_f32_e32 v71, v71
	s_nop 0
	v_add_f32_e32 v68, 1.0, v71
	v_rcp_f32_e32 v72, v68
	v_mul_f32_e32 v66, v60, v69
	v_mov_b32_e32 v60, v66
	v_mul_f32_e32 v56, v60, v56
	v_mul_f32_e32 v67, 0xbfb8aa3b, v62
	v_exp_f32_e32 v67, v67
	v_mul_f32_e32 v60, v61, v72
	v_add_f32_e32 v66, 1.0, v67
	v_rcp_f32_e32 v69, v66
	v_mul_f32_e32 v57, v60, v57
	v_mul_f32_e32 v61, 0xbfb8aa3b, v63
	s_nop 0
	v_cvt_pk_bf16_f32 v56, v56, v57
	v_exp_f32_e32 v61, v61
	s_nop 0
	v_add_f32_e32 v61, 1.0, v61
	v_rcp_f32_e32 v68, v61
	v_mul_f32_e32 v57, v62, v69
	v_mul_f32_e32 v57, v57, v58
	v_mul_f32_e32 v58, v63, v68
	v_mul_f32_e32 v60, 0xbfb8aa3b, v52
	v_exp_f32_e32 v60, v60
	v_mul_f32_e32 v58, v58, v59
	v_cvt_pk_bf16_f32 v57, v57, v58
	v_add_f32_e32 v60, 1.0, v60
	v_rcp_f32_e32 v62, v60
	v_add_co_u32_e32 v58, vcc, s78, v128
	v_lshl_add_u64 v[64:65], v[128:129], 0, s[42:43]
	s_nop 0
	v_addc_co_u32_e32 v59, vcc, 0, v129, vcc
	global_store_dwordx2 v[58:59], v[56:57], off
	v_mul_f32_e32 v58, 0xbfb8aa3b, v53
	v_exp_f32_e32 v58, v58
	s_nop 0
	v_add_f32_e32 v58, 1.0, v58
	v_rcp_f32_e32 v61, v58
	v_mul_f32_e32 v56, v52, v62
	v_mov_b32_e32 v52, v56
	v_mul_f32_e32 v48, v52, v48
	v_mul_f32_e32 v57, 0xbfb8aa3b, v54
	v_exp_f32_e32 v57, v57
	v_mul_f32_e32 v52, v53, v61
	v_add_f32_e32 v56, 1.0, v57
	v_rcp_f32_e32 v59, v56
	v_mul_f32_e32 v49, v52, v49
	v_mul_f32_e32 v53, 0xbfb8aa3b, v55
	v_cvt_pk_bf16_f32 v48, v48, v49
	v_exp_f32_e32 v53, v53
	s_nop 0
	v_add_f32_e32 v53, 1.0, v53
	v_rcp_f32_e32 v58, v53
	v_mul_f32_e32 v49, v54, v59
	v_mul_f32_e32 v49, v49, v50
	v_mul_f32_e32 v54, 0xbfb8aa3b, v44
	v_exp_f32_e32 v54, v54
	v_mul_f32_e32 v50, v55, v58
	v_mul_f32_e32 v50, v50, v51
	v_add_f32_e32 v51, 1.0, v54
	v_rcp_f32_e32 v53, v51
	v_cvt_pk_bf16_f32 v49, v49, v50
	v_mul_f32_e32 v55, 0xbfb8aa3b, v45
	v_exp_f32_e32 v55, v55
	s_nop 0
	v_add_f32_e32 v52, 1.0, v55
	v_rcp_f32_e32 v56, v52
	v_mul_f32_e32 v50, v44, v53
	v_mov_b32_e32 v44, v50
	v_mul_f32_e32 v40, v44, v40
	v_mul_f32_e32 v51, 0xbfb8aa3b, v46
	v_exp_f32_e32 v51, v51
	v_mul_f32_e32 v44, v45, v56
	v_add_f32_e32 v50, 1.0, v51
	v_rcp_f32_e32 v53, v50
	v_mul_f32_e32 v41, v44, v41
	v_mul_f32_e32 v45, 0xbfb8aa3b, v47
	global_store_dwordx2 v[64:65], v[48:49], off offset:32
	v_cvt_pk_bf16_f32 v40, v40, v41
	v_exp_f32_e32 v45, v45
	s_nop 0
	v_add_f32_e32 v45, 1.0, v45
	v_rcp_f32_e32 v52, v45
	v_mul_f32_e32 v41, v46, v53
	v_mul_f32_e32 v41, v41, v42
	v_mul_f32_e32 v42, v47, v52
	v_mul_f32_e32 v44, 0xbfb8aa3b, v36
	v_exp_f32_e32 v44, v44
	v_mul_f32_e32 v42, v42, v43
	v_cvt_pk_bf16_f32 v41, v41, v42
	v_add_f32_e32 v44, 1.0, v44
	v_rcp_f32_e32 v46, v44
	v_add_co_u32_e32 v42, vcc, s79, v128
	v_lshl_add_u64 v[48:49], v[128:129], 0, s[44:45]
	s_nop 0
	v_addc_co_u32_e32 v43, vcc, 0, v129, vcc
	global_store_dwordx2 v[42:43], v[40:41], off
	v_mul_f32_e32 v42, 0xbfb8aa3b, v37
	v_exp_f32_e32 v42, v42
	s_nop 0
	v_add_f32_e32 v42, 1.0, v42
	v_rcp_f32_e32 v45, v42
	v_mul_f32_e32 v40, v36, v46
	v_mov_b32_e32 v36, v40
	v_mul_f32_e32 v32, v36, v32
	v_mul_f32_e32 v41, 0xbfb8aa3b, v38
	v_exp_f32_e32 v41, v41
	v_mul_f32_e32 v36, v37, v45
	v_add_f32_e32 v40, 1.0, v41
	v_rcp_f32_e32 v43, v40
	v_mul_f32_e32 v33, v36, v33
	v_mul_f32_e32 v37, 0xbfb8aa3b, v39
	v_cvt_pk_bf16_f32 v32, v32, v33
	v_exp_f32_e32 v37, v37
	s_nop 0
	v_add_f32_e32 v37, 1.0, v37
	v_rcp_f32_e32 v42, v37
	v_mul_f32_e32 v33, v38, v43
	v_mul_f32_e32 v33, v33, v34
	v_mul_f32_e32 v38, 0xbfb8aa3b, v28
	v_exp_f32_e32 v38, v38
	v_mul_f32_e32 v34, v39, v42
	v_mul_f32_e32 v34, v34, v35
	v_add_f32_e32 v35, 1.0, v38
	v_rcp_f32_e32 v37, v35
	v_cvt_pk_bf16_f32 v33, v33, v34
	v_mul_f32_e32 v39, 0xbfb8aa3b, v29
	v_exp_f32_e32 v39, v39
	s_nop 0
	v_add_f32_e32 v36, 1.0, v39
	v_rcp_f32_e32 v40, v36
	v_mul_f32_e32 v34, v28, v37
	v_mov_b32_e32 v28, v34
	v_mul_f32_e32 v24, v28, v24
	v_mul_f32_e32 v35, 0xbfb8aa3b, v30
	v_exp_f32_e32 v35, v35
	v_mul_f32_e32 v28, v29, v40
	v_add_f32_e32 v34, 1.0, v35
	v_rcp_f32_e32 v37, v34
	v_mul_f32_e32 v25, v28, v25
	v_mul_f32_e32 v29, 0xbfb8aa3b, v31
	global_store_dwordx2 v[48:49], v[32:33], off offset:32
	v_cvt_pk_bf16_f32 v24, v24, v25
	v_exp_f32_e32 v29, v29
	s_nop 0
	v_add_f32_e32 v29, 1.0, v29
	v_rcp_f32_e32 v36, v29
	v_mul_f32_e32 v25, v30, v37
	v_mul_f32_e32 v25, v25, v26
	v_mul_f32_e32 v26, v31, v36
	v_mul_f32_e32 v28, 0xbfb8aa3b, v20
	v_exp_f32_e32 v28, v28
	v_mul_f32_e32 v26, v26, v27
	v_cvt_pk_bf16_f32 v25, v25, v26
	v_add_f32_e32 v28, 1.0, v28
	v_rcp_f32_e32 v30, v28
	v_add_co_u32_e32 v26, vcc, s80, v128
	v_lshl_add_u64 v[32:33], v[128:129], 0, s[46:47]
	s_nop 0
	v_addc_co_u32_e32 v27, vcc, 0, v129, vcc
	global_store_dwordx2 v[26:27], v[24:25], off
	v_mul_f32_e32 v26, 0xbfb8aa3b, v21
	v_exp_f32_e32 v26, v26
	s_nop 0
	v_add_f32_e32 v26, 1.0, v26
	v_rcp_f32_e32 v29, v26
	v_mul_f32_e32 v24, v20, v30
	v_mov_b32_e32 v20, v24
	v_mul_f32_e32 v16, v20, v16
	v_mul_f32_e32 v25, 0xbfb8aa3b, v22
	v_exp_f32_e32 v25, v25
	v_mul_f32_e32 v20, v21, v29
	v_add_f32_e32 v24, 1.0, v25
	v_rcp_f32_e32 v27, v24
	v_mul_f32_e32 v17, v20, v17
	v_mul_f32_e32 v21, 0xbfb8aa3b, v23
	v_cvt_pk_bf16_f32 v16, v16, v17
	v_exp_f32_e32 v21, v21
	s_nop 0
	v_add_f32_e32 v21, 1.0, v21
	v_rcp_f32_e32 v26, v21
	v_mul_f32_e32 v17, v22, v27
	v_mul_f32_e32 v17, v17, v18
	v_mul_f32_e32 v22, 0xbfb8aa3b, v12
	v_exp_f32_e32 v22, v22
	v_mul_f32_e32 v18, v23, v26
	v_mul_f32_e32 v18, v18, v19
	v_add_f32_e32 v19, 1.0, v22
	v_rcp_f32_e32 v21, v19
	v_cvt_pk_bf16_f32 v17, v17, v18
	v_mul_f32_e32 v23, 0xbfb8aa3b, v13
	v_exp_f32_e32 v23, v23
	s_nop 0
	v_add_f32_e32 v20, 1.0, v23
	v_rcp_f32_e32 v24, v20
	v_mul_f32_e32 v18, v12, v21
	v_mov_b32_e32 v12, v18
	v_mul_f32_e32 v8, v12, v8
	v_mul_f32_e32 v19, 0xbfb8aa3b, v14
	v_exp_f32_e32 v19, v19
	v_mul_f32_e32 v12, v13, v24
	v_add_f32_e32 v18, 1.0, v19
	v_rcp_f32_e32 v21, v18
	v_mul_f32_e32 v9, v12, v9
	v_mul_f32_e32 v13, 0xbfb8aa3b, v15
	global_store_dwordx2 v[32:33], v[16:17], off offset:32
	v_cvt_pk_bf16_f32 v8, v8, v9
	v_exp_f32_e32 v13, v13
	s_nop 0
	v_add_f32_e32 v13, 1.0, v13
	v_rcp_f32_e32 v20, v13
	v_mul_f32_e32 v9, v14, v21
	v_mul_f32_e32 v9, v9, v10
	v_mul_f32_e32 v10, v15, v20
	v_mul_f32_e32 v12, 0xbfb8aa3b, v4
	v_exp_f32_e32 v12, v12
	v_mul_f32_e32 v10, v10, v11
	v_cvt_pk_bf16_f32 v9, v9, v10
	v_add_f32_e32 v12, 1.0, v12
	v_rcp_f32_e32 v14, v12
	v_add_co_u32_e32 v10, vcc, s81, v128
	v_lshl_add_u64 v[16:17], v[128:129], 0, s[48:49]
	s_nop 0
	v_addc_co_u32_e32 v11, vcc, 0, v129, vcc
	global_store_dwordx2 v[10:11], v[8:9], off
	v_mul_f32_e32 v10, 0xbfb8aa3b, v5
	v_exp_f32_e32 v10, v10
	s_nop 0
	v_add_f32_e32 v10, 1.0, v10
	v_rcp_f32_e32 v13, v10
	v_mul_f32_e32 v8, v4, v14
	v_mov_b32_e32 v4, v8
	v_mul_f32_e32 v0, v4, v0
	v_mul_f32_e32 v9, 0xbfb8aa3b, v6
	v_exp_f32_e32 v9, v9
	v_mul_f32_e32 v4, v5, v13
	v_add_f32_e32 v8, 1.0, v9
	v_rcp_f32_e32 v11, v8
	v_mul_f32_e32 v1, v4, v1
	v_mul_f32_e32 v5, 0xbfb8aa3b, v7
	v_cvt_pk_bf16_f32 v0, v0, v1
	v_exp_f32_e32 v5, v5
	s_nop 0
	v_add_f32_e32 v5, 1.0, v5
	v_rcp_f32_e32 v10, v5
	v_mul_f32_e32 v1, v6, v11
	v_mul_f32_e32 v1, v1, v2
	v_mul_f32_e32 v2, v7, v10
	v_mul_f32_e32 v2, v2, v3
	v_cvt_pk_bf16_f32 v1, v1, v2
	global_store_dwordx2 v[16:17], v[0:1], off offset:32
	s_and_b64 vcc, exec, s[4:5]
	v_mov_b32_e32 v4, v180
	s_mov_b32 s82, s50
	v_mov_b32_e32 v198, v192
	v_mov_b64_e32 v[2:3], v[196:197]
	v_mov_b64_e32 v[0:1], v[194:195]
	s_branch .LBB0_1752

.LBB0_1809:
	s_or_b64 exec, exec, s[6:7]
	s_add_i32 s3, 0, 0x22080
	v_mov_b32_e32 v0, s3
	s_waitcnt lgkmcnt(0)
	s_barrier
	ds_read_b32 v0, v0
	s_load_dword s3, s[0:1], 0x230
	s_add_u32 s6, s0, 0x230
	s_addc_u32 s7, s1, 0
	v_readfirstlane_b32 s46, v13
	s_waitcnt lgkmcnt(0)
	v_cmp_ge_i32_e32 vcc, s2, v0
	v_readfirstlane_b32 s20, v0
	s_mov_b32 s92, s20
	s_lshr_b32 s93, s92, 8
	s_and_b32 s94, s92, 0xff
	s_sub_i32 s95, 0x100, s94
	s_min_u32 s95, s95, s94
	s_cmp_eq_u32 s3, 0x100
	s_cselect_b32 s93, s93, 0x7fffffff
	s_cmp_eq_u32 s93, 0
	s_cselect_b32 s93, 0x7fffffff, s93
	s_mov_b32 s90, 3
	s_mov_b32 s91, 3
	s_cbranch_vccnz .LBB0_1837
	s_ashr_i32 s21, s20, 31
	s_lshr_b32 s8, s21, 29
	s_add_i32 s8, s20, s8
	s_ashr_i32 s47, s8, 3
	s_and_b32 s8, s8, -8
	s_ashr_i32 s49, s2, 31
	s_sub_i32 s48, s20, s8
	s_lshr_b32 s8, s49, 29
	s_add_i32 s11, s2, s8
	s_and_b32 s8, s11, -8
	s_sub_i32 s10, s2, s8
	s_add_i32 s50, s47, 1
	s_cmp_ge_i32 s10, s48
	s_mul_i32 s51, s50, s48
	s_cbranch_scc0 .LBB0_1812
	s_sub_i32 s8, s10, s48
	s_mul_i32 s8, s8, s47
	s_add_i32 s12, s8, s51
	s_load_dwordx2 s[14:15], s[4:5], 0x1d8
	s_ashr_i32 s13, s11, 3
	s_cbranch_execz .LBB0_1813
	s_branch .LBB0_1814

.LBB0_1832:
	v_add_u32_e32 v128, s65, v155
	ds_read_b128 v[158:161], v128
	ds_read_b128 v[162:165], v128 offset:1024
	ds_read_b128 v[166:169], v128 offset:2048
	ds_read_b128 v[170:173], v128 offset:3072
	s_cmp_eq_u32 s44, 12
	v_lshl_add_u64 v[152:153], v[148:149], 0, s[22:23]
	s_cselect_b64 vcc, -1, 0
	v_cndmask_b32_e32 v207, v153, v147, vcc
	v_cndmask_b32_e32 v206, v152, v146, vcc
	v_cndmask_b32_e32 v153, v151, v145, vcc
	v_cndmask_b32_e32 v152, v150, v144, vcc
	v_lshl_add_u64 v[210:211], v[148:149], 0, v[134:135]
	s_add_i32 m0, s53, 0xc000
	ds_read_b128 v[174:177], v157
	ds_read_b128 v[178:181], v157 offset:1024
	ds_read_b128 v[182:185], v157 offset:2048
	ds_read_b128 v[186:189], v157 offset:3072
	ds_read_b128 v[190:193], v157 offset:4096
	ds_read_b128 v[194:197], v157 offset:5120
	ds_read_b128 v[198:201], v157 offset:6144
	ds_read_b128 v[202:205], v157 offset:7168
	global_load_lds_dwordx4 v[210:211], off
	v_lshl_add_u64 v[210:211], v[148:149], 0, v[136:137]
	s_add_i32 m0, s53, 0xe000
	s_nop 0
	global_load_lds_dwordx4 v[210:211], off
	s_waitcnt lgkmcnt(8)
	s_barrier
	s_waitcnt lgkmcnt(0)
	s_setprio 1
	s_waitcnt lgkmcnt(0)
	v_mfma_f32_16x16x32_bf16 v[124:127], v[158:161], v[174:177], v[124:127]
	v_mfma_f32_16x16x32_bf16 v[120:123], v[166:169], v[174:177], v[120:123]
	v_mfma_f32_16x16x32_bf16 v[116:119], v[158:161], v[182:185], v[116:119]
	v_mfma_f32_16x16x32_bf16 v[108:111], v[166:169], v[182:185], v[108:111]
	v_mfma_f32_16x16x32_bf16 v[100:103], v[158:161], v[190:193], v[100:103]
	v_mfma_f32_16x16x32_bf16 v[92:95], v[166:169], v[190:193], v[92:95]
	v_mfma_f32_16x16x32_bf16 v[84:87], v[158:161], v[198:201], v[84:87]
	v_mfma_f32_16x16x32_bf16 v[76:79], v[166:169], v[198:201], v[76:79]
	v_mfma_f32_16x16x32_bf16 v[124:127], v[162:165], v[178:181], v[124:127]
	v_mfma_f32_16x16x32_bf16 v[120:123], v[170:173], v[178:181], v[120:123]
	v_mfma_f32_16x16x32_bf16 v[116:119], v[162:165], v[186:189], v[116:119]
	v_mfma_f32_16x16x32_bf16 v[108:111], v[170:173], v[186:189], v[108:111]
	v_mfma_f32_16x16x32_bf16 v[100:103], v[162:165], v[194:197], v[100:103]
	v_mfma_f32_16x16x32_bf16 v[92:95], v[170:173], v[194:197], v[92:95]
	v_mfma_f32_16x16x32_bf16 v[84:87], v[162:165], v[202:205], v[84:87]
	v_mfma_f32_16x16x32_bf16 v[76:79], v[170:173], v[202:205], v[76:79]
	s_setprio 0
	s_barrier
	s_add_i32 s45, s65, s52
	v_add_u32_e32 v128, s66, v155
	v_lshl_add_u64 v[226:227], v[152:153], 0, v[130:131]
	s_mov_b32 m0, s45
	ds_read_b128 v[210:213], v128
	ds_read_b128 v[214:217], v128 offset:1024
	ds_read_b128 v[218:221], v128 offset:2048
	ds_read_b128 v[222:225], v128 offset:3072
	global_load_lds_dwordx4 v[226:227], off
	v_lshl_add_u64 v[228:229], v[152:153], 0, v[132:133]
	s_add_i32 m0, s45, 0x2000
	s_nop 0
	global_load_lds_dwordx4 v[228:229], off
	s_barrier
	s_waitcnt lgkmcnt(0)
	s_setprio 1
	s_waitcnt lgkmcnt(0)
	v_mfma_f32_16x16x32_bf16 v[112:115], v[210:213], v[174:177], v[112:115]
	v_mfma_f32_16x16x32_bf16 v[104:107], v[218:221], v[174:177], v[104:107]
	v_mfma_f32_16x16x32_bf16 v[96:99], v[210:213], v[182:185], v[96:99]
	v_mfma_f32_16x16x32_bf16 v[88:91], v[218:221], v[182:185], v[88:91]
	v_mfma_f32_16x16x32_bf16 v[80:83], v[210:213], v[190:193], v[80:83]
	v_mfma_f32_16x16x32_bf16 v[72:75], v[218:221], v[190:193], v[72:75]
	v_mfma_f32_16x16x32_bf16 v[68:71], v[210:213], v[198:201], v[68:71]
	v_mfma_f32_16x16x32_bf16 v[64:67], v[218:221], v[198:201], v[64:67]
	v_mfma_f32_16x16x32_bf16 v[112:115], v[214:217], v[178:181], v[112:115]
	v_mfma_f32_16x16x32_bf16 v[104:107], v[222:225], v[178:181], v[104:107]
	v_mfma_f32_16x16x32_bf16 v[96:99], v[214:217], v[186:189], v[96:99]
	v_mfma_f32_16x16x32_bf16 v[88:91], v[222:225], v[186:189], v[88:91]
	v_mfma_f32_16x16x32_bf16 v[80:83], v[214:217], v[194:197], v[80:83]
	v_mfma_f32_16x16x32_bf16 v[72:75], v[222:225], v[194:197], v[72:75]
	v_mfma_f32_16x16x32_bf16 v[68:71], v[214:217], v[202:205], v[68:71]
	v_mfma_f32_16x16x32_bf16 v[64:67], v[222:225], v[202:205], v[64:67]
	s_setprio 0
	s_mov_b32 m0, s53
	v_lshl_add_u64 v[230:231], v[206:207], 0, v[130:131]
	s_barrier
	ds_read_b128 v[174:177], v157 offset:16384
	ds_read_b128 v[178:181], v157 offset:17408
	ds_read_b128 v[182:185], v157 offset:18432
	ds_read_b128 v[186:189], v157 offset:19456
	ds_read_b128 v[190:193], v157 offset:20480
	ds_read_b128 v[194:197], v157 offset:21504
	ds_read_b128 v[198:201], v157 offset:22528
	ds_read_b128 v[202:205], v157 offset:23552
	global_load_lds_dwordx4 v[230:231], off
	v_lshl_add_u64 v[232:233], v[206:207], 0, v[132:133]
	s_mov_b32 m0, s54
	s_nop 0
	global_load_lds_dwordx4 v[232:233], off
	s_barrier
	s_waitcnt lgkmcnt(0)
	s_setprio 1
	s_waitcnt lgkmcnt(0)
	v_mfma_f32_16x16x32_bf16 v[60:63], v[158:161], v[174:177], v[60:63]
	v_mfma_f32_16x16x32_bf16 v[56:59], v[166:169], v[174:177], v[56:59]
	v_mfma_f32_16x16x32_bf16 v[52:55], v[158:161], v[182:185], v[52:55]
	v_mfma_f32_16x16x32_bf16 v[44:47], v[166:169], v[182:185], v[44:47]
	v_mfma_f32_16x16x32_bf16 v[36:39], v[158:161], v[190:193], v[36:39]
	v_mfma_f32_16x16x32_bf16 v[28:31], v[166:169], v[190:193], v[28:31]
	v_mfma_f32_16x16x32_bf16 v[20:23], v[158:161], v[198:201], v[20:23]
	v_mfma_f32_16x16x32_bf16 v[12:15], v[166:169], v[198:201], v[12:15]
	v_mfma_f32_16x16x32_bf16 v[60:63], v[162:165], v[178:181], v[60:63]
	v_mfma_f32_16x16x32_bf16 v[56:59], v[170:173], v[178:181], v[56:59]
	v_mfma_f32_16x16x32_bf16 v[52:55], v[162:165], v[186:189], v[52:55]
	v_mfma_f32_16x16x32_bf16 v[44:47], v[170:173], v[186:189], v[44:47]
	v_mfma_f32_16x16x32_bf16 v[36:39], v[162:165], v[194:197], v[36:39]
	v_mfma_f32_16x16x32_bf16 v[28:31], v[170:173], v[194:197], v[28:31]
	v_mfma_f32_16x16x32_bf16 v[20:23], v[162:165], v[202:205], v[20:23]
	v_mfma_f32_16x16x32_bf16 v[12:15], v[170:173], v[202:205], v[12:15]
	s_setprio 0
	s_barrier
	v_lshl_add_u64 v[158:159], v[152:153], 0, s[12:13]
	s_add_i32 s45, s66, s52
	v_lshl_add_u64 v[160:161], v[158:159], 0, v[130:131]
	s_mov_b32 m0, s45
	v_lshl_add_u64 v[158:159], v[158:159], 0, v[132:133]
	global_load_lds_dwordx4 v[160:161], off
	s_add_i32 m0, s45, 0x2000
	s_nop 0
	global_load_lds_dwordx4 v[158:159], off
	s_waitcnt vmcnt(6)
	s_barrier
	s_setprio 1
	v_mfma_f32_16x16x32_bf16 v[48:51], v[210:213], v[174:177], v[48:51]
	v_mfma_f32_16x16x32_bf16 v[40:43], v[218:221], v[174:177], v[40:43]
	v_mfma_f32_16x16x32_bf16 v[32:35], v[210:213], v[182:185], v[32:35]
	v_mfma_f32_16x16x32_bf16 v[24:27], v[218:221], v[182:185], v[24:27]
	v_mfma_f32_16x16x32_bf16 v[16:19], v[210:213], v[190:193], v[16:19]
	v_mfma_f32_16x16x32_bf16 v[8:11], v[218:221], v[190:193], v[8:11]
	v_mfma_f32_16x16x32_bf16 v[4:7], v[210:213], v[198:201], v[4:7]
	v_mfma_f32_16x16x32_bf16 v[0:3], v[218:221], v[198:201], v[0:3]
	v_mfma_f32_16x16x32_bf16 v[48:51], v[214:217], v[178:181], v[48:51]
	v_mfma_f32_16x16x32_bf16 v[40:43], v[222:225], v[178:181], v[40:43]
	v_mfma_f32_16x16x32_bf16 v[32:35], v[214:217], v[186:189], v[32:35]
	v_mfma_f32_16x16x32_bf16 v[24:27], v[222:225], v[186:189], v[24:27]
	v_mfma_f32_16x16x32_bf16 v[16:19], v[214:217], v[194:197], v[16:19]
	v_mfma_f32_16x16x32_bf16 v[8:11], v[222:225], v[194:197], v[8:11]
	v_mfma_f32_16x16x32_bf16 v[4:7], v[214:217], v[202:205], v[4:7]
	v_mfma_f32_16x16x32_bf16 v[0:3], v[222:225], v[202:205], v[0:3]
	s_setprio 0
	s_add_i32 s45, 0, 0x18000
	v_add_u32_e32 v128, s45, v155
	s_barrier
	ds_read_b128 v[158:161], v128
	ds_read_b128 v[162:165], v128 offset:1024
	ds_read_b128 v[166:169], v128 offset:2048
	ds_read_b128 v[170:173], v128 offset:3072
	v_lshl_add_u64 v[206:207], v[206:207], 0, s[12:13]
	s_mov_b32 m0, s55
	v_lshl_add_u64 v[210:211], v[206:207], 0, v[130:131]
	ds_read_b128 v[174:177], v157 offset:32768
	ds_read_b128 v[178:181], v157 offset:33792
	ds_read_b128 v[182:185], v157 offset:34816
	ds_read_b128 v[186:189], v157 offset:35840
	ds_read_b128 v[190:193], v157 offset:36864
	ds_read_b128 v[194:197], v157 offset:37888
	ds_read_b128 v[198:201], v157 offset:38912
	ds_read_b128 v[202:205], v157 offset:39936
	global_load_lds_dwordx4 v[210:211], off
	v_lshl_add_u64 v[206:207], v[206:207], 0, v[132:133]
	s_mov_b32 m0, s56
	s_nop 0
	global_load_lds_dwordx4 v[206:207], off
	s_waitcnt lgkmcnt(8)
	s_barrier
	s_waitcnt lgkmcnt(0)
	s_setprio 1
	s_waitcnt lgkmcnt(0)
	v_mfma_f32_16x16x32_bf16 v[124:127], v[158:161], v[174:177], v[124:127]
	v_mfma_f32_16x16x32_bf16 v[120:123], v[166:169], v[174:177], v[120:123]
	v_mfma_f32_16x16x32_bf16 v[116:119], v[158:161], v[182:185], v[116:119]
	v_mfma_f32_16x16x32_bf16 v[108:111], v[166:169], v[182:185], v[108:111]
	v_mfma_f32_16x16x32_bf16 v[100:103], v[158:161], v[190:193], v[100:103]
	v_mfma_f32_16x16x32_bf16 v[92:95], v[166:169], v[190:193], v[92:95]
	v_mfma_f32_16x16x32_bf16 v[84:87], v[158:161], v[198:201], v[84:87]
	v_mfma_f32_16x16x32_bf16 v[76:79], v[166:169], v[198:201], v[76:79]
	v_mfma_f32_16x16x32_bf16 v[124:127], v[162:165], v[178:181], v[124:127]
	v_mfma_f32_16x16x32_bf16 v[120:123], v[170:173], v[178:181], v[120:123]
	v_mfma_f32_16x16x32_bf16 v[116:119], v[162:165], v[186:189], v[116:119]
	v_mfma_f32_16x16x32_bf16 v[108:111], v[170:173], v[186:189], v[108:111]
	v_mfma_f32_16x16x32_bf16 v[100:103], v[162:165], v[194:197], v[100:103]
	v_mfma_f32_16x16x32_bf16 v[92:95], v[170:173], v[194:197], v[92:95]
	v_mfma_f32_16x16x32_bf16 v[84:87], v[162:165], v[202:205], v[84:87]
	v_mfma_f32_16x16x32_bf16 v[76:79], v[170:173], v[202:205], v[76:79]
	s_setprio 0
	s_barrier
	s_add_i32 s75, 0, 0x1c000
	s_add_i32 s45, s45, s52
	v_add_u32_e32 v128, s75, v155
	v_lshl_add_u64 v[206:207], v[226:227], 0, s[16:17]
	s_mov_b32 m0, s45
	ds_read_b128 v[210:213], v128
	ds_read_b128 v[214:217], v128 offset:1024
	ds_read_b128 v[218:221], v128 offset:2048
	ds_read_b128 v[222:225], v128 offset:3072
	global_load_lds_dwordx4 v[206:207], off
	v_lshl_add_u64 v[206:207], v[228:229], 0, s[16:17]
	s_add_i32 m0, s45, 0x2000
	s_nop 0
	global_load_lds_dwordx4 v[206:207], off
	s_barrier
	s_waitcnt lgkmcnt(0)
	s_setprio 1
	s_waitcnt lgkmcnt(0)
	v_mfma_f32_16x16x32_bf16 v[112:115], v[210:213], v[174:177], v[112:115]
	v_mfma_f32_16x16x32_bf16 v[104:107], v[218:221], v[174:177], v[104:107]
	v_mfma_f32_16x16x32_bf16 v[96:99], v[210:213], v[182:185], v[96:99]
	v_mfma_f32_16x16x32_bf16 v[88:91], v[218:221], v[182:185], v[88:91]
	v_mfma_f32_16x16x32_bf16 v[80:83], v[210:213], v[190:193], v[80:83]
	v_mfma_f32_16x16x32_bf16 v[72:75], v[218:221], v[190:193], v[72:75]
	v_mfma_f32_16x16x32_bf16 v[68:71], v[210:213], v[198:201], v[68:71]
	v_mfma_f32_16x16x32_bf16 v[64:67], v[218:221], v[198:201], v[64:67]
	v_mfma_f32_16x16x32_bf16 v[112:115], v[214:217], v[178:181], v[112:115]
	v_mfma_f32_16x16x32_bf16 v[104:107], v[222:225], v[178:181], v[104:107]
	v_mfma_f32_16x16x32_bf16 v[96:99], v[214:217], v[186:189], v[96:99]
	v_mfma_f32_16x16x32_bf16 v[88:91], v[222:225], v[186:189], v[88:91]
	v_mfma_f32_16x16x32_bf16 v[80:83], v[214:217], v[194:197], v[80:83]
	v_mfma_f32_16x16x32_bf16 v[72:75], v[222:225], v[194:197], v[72:75]
	v_mfma_f32_16x16x32_bf16 v[68:71], v[214:217], v[202:205], v[68:71]
	v_mfma_f32_16x16x32_bf16 v[64:67], v[222:225], v[202:205], v[64:67]
	s_setprio 0
	s_mov_b32 m0, s59
	v_lshl_add_u64 v[206:207], v[230:231], 0, s[16:17]
	s_barrier
	ds_read_b128 v[174:177], v157 offset:49152
	ds_read_b128 v[178:181], v157 offset:50176
	ds_read_b128 v[182:185], v157 offset:51200
	ds_read_b128 v[186:189], v157 offset:52224
	ds_read_b128 v[190:193], v157 offset:53248
	ds_read_b128 v[194:197], v157 offset:54272
	ds_read_b128 v[198:201], v157 offset:55296
	ds_read_b128 v[202:205], v157 offset:56320
	global_load_lds_dwordx4 v[206:207], off
	v_lshl_add_u64 v[206:207], v[232:233], 0, s[16:17]
	s_mov_b32 m0, s60
	s_nop 0
	global_load_lds_dwordx4 v[206:207], off
	s_barrier
	s_waitcnt lgkmcnt(0)
	s_setprio 1
	s_waitcnt lgkmcnt(0)
	v_mfma_f32_16x16x32_bf16 v[60:63], v[158:161], v[174:177], v[60:63]
	v_mfma_f32_16x16x32_bf16 v[56:59], v[166:169], v[174:177], v[56:59]
	v_mfma_f32_16x16x32_bf16 v[52:55], v[158:161], v[182:185], v[52:55]
	v_mfma_f32_16x16x32_bf16 v[44:47], v[166:169], v[182:185], v[44:47]
	v_mfma_f32_16x16x32_bf16 v[36:39], v[158:161], v[190:193], v[36:39]
	v_mfma_f32_16x16x32_bf16 v[28:31], v[166:169], v[190:193], v[28:31]
	v_mfma_f32_16x16x32_bf16 v[20:23], v[158:161], v[198:201], v[20:23]
	v_mfma_f32_16x16x32_bf16 v[12:15], v[166:169], v[198:201], v[12:15]
	v_mfma_f32_16x16x32_bf16 v[60:63], v[162:165], v[178:181], v[60:63]
	v_mfma_f32_16x16x32_bf16 v[56:59], v[170:173], v[178:181], v[56:59]
	v_mfma_f32_16x16x32_bf16 v[52:55], v[162:165], v[186:189], v[52:55]
	v_mfma_f32_16x16x32_bf16 v[44:47], v[170:173], v[186:189], v[44:47]
	v_mfma_f32_16x16x32_bf16 v[36:39], v[162:165], v[194:197], v[36:39]
	v_mfma_f32_16x16x32_bf16 v[28:31], v[170:173], v[194:197], v[28:31]
	v_mfma_f32_16x16x32_bf16 v[20:23], v[162:165], v[202:205], v[20:23]
	v_mfma_f32_16x16x32_bf16 v[12:15], v[170:173], v[202:205], v[12:15]
	s_setprio 0
	s_barrier
	v_lshl_add_u64 v[152:153], v[152:153], 0, s[18:19]
	s_add_i32 s45, s75, s52
	v_lshl_add_u64 v[158:159], v[152:153], 0, v[130:131]
	s_mov_b32 m0, s45
	v_lshl_add_u64 v[152:153], v[152:153], 0, v[132:133]
	global_load_lds_dwordx4 v[158:159], off
	s_add_i32 m0, s45, 0x2000
	s_nop 0
	global_load_lds_dwordx4 v[152:153], off
	s_waitcnt vmcnt(6)
	s_barrier
	s_setprio 1
	v_mfma_f32_16x16x32_bf16 v[48:51], v[210:213], v[174:177], v[48:51]
	v_mfma_f32_16x16x32_bf16 v[40:43], v[218:221], v[174:177], v[40:43]
	v_mfma_f32_16x16x32_bf16 v[32:35], v[210:213], v[182:185], v[32:35]
	v_mfma_f32_16x16x32_bf16 v[24:27], v[218:221], v[182:185], v[24:27]
	v_mfma_f32_16x16x32_bf16 v[16:19], v[210:213], v[190:193], v[16:19]
	v_mfma_f32_16x16x32_bf16 v[8:11], v[218:221], v[190:193], v[8:11]
	v_mfma_f32_16x16x32_bf16 v[4:7], v[210:213], v[198:201], v[4:7]
	v_mfma_f32_16x16x32_bf16 v[0:3], v[218:221], v[198:201], v[0:3]
	v_mfma_f32_16x16x32_bf16 v[48:51], v[214:217], v[178:181], v[48:51]
	v_mfma_f32_16x16x32_bf16 v[40:43], v[222:225], v[178:181], v[40:43]
	v_mfma_f32_16x16x32_bf16 v[32:35], v[214:217], v[186:189], v[32:35]
	v_mfma_f32_16x16x32_bf16 v[24:27], v[222:225], v[186:189], v[24:27]
	v_mfma_f32_16x16x32_bf16 v[16:19], v[214:217], v[194:197], v[16:19]
	v_mfma_f32_16x16x32_bf16 v[8:11], v[222:225], v[194:197], v[8:11]
	v_mfma_f32_16x16x32_bf16 v[4:7], v[214:217], v[202:205], v[4:7]
	v_mfma_f32_16x16x32_bf16 v[0:3], v[222:225], v[202:205], v[0:3]
	s_setprio 0
	s_add_i32 s44, s44, 2
	v_lshl_add_u64 v[148:149], v[148:149], 0, s[20:21]
	s_cmp_gt_u32 s44, 13
	v_lshl_add_u64 v[150:151], v[150:151], 0, s[20:21]
	s_barrier
	s_cbranch_scc0 .LBB0_1832
	v_add_u32_e32 v140, v140, v154
	v_ashrrev_i32_e32 v141, 31, v140
	v_add_u32_e32 v148, s74, v156
	v_lshlrev_b64 v[140:141], 12, v[140:141]
	v_ashrrev_i32_e32 v149, 31, v148
	v_lshl_add_u64 v[140:141], s[14:15], 0, v[140:141]
	v_add_f32_e32 v124, 0, v124
	v_add_f32_e32 v125, 0, v125
	v_lshl_add_u64 v[140:141], v[148:149], 1, v[140:141]
	v_cvt_pk_bf16_f32 v124, v124, v125
	v_add_f32_e32 v125, 0, v126
	v_add_f32_e32 v120, 0, v120
	v_add_f32_e32 v121, 0, v121
	v_add_f32_e32 v126, 0, v127
	v_cvt_pk_bf16_f32 v125, v125, v126
	global_store_dwordx2 v[140:141], v[124:125], off
	v_cvt_pk_bf16_f32 v120, v120, v121
	v_add_f32_e32 v121, 0, v122
	v_add_f32_e32 v112, 0, v112
	v_add_f32_e32 v113, 0, v113
	v_add_f32_e32 v122, 0, v123
	v_cvt_pk_bf16_f32 v121, v121, v122
	global_store_dwordx2 v[140:141], v[120:121], off offset:32
	v_cvt_pk_bf16_f32 v112, v112, v113
	v_add_f32_e32 v113, 0, v114
	v_add_f32_e32 v104, 0, v104
	v_add_f32_e32 v105, 0, v105
	v_add_f32_e32 v114, 0, v115
	v_cvt_pk_bf16_f32 v113, v113, v114
	global_store_dwordx2 v[140:141], v[112:113], off offset:256
	v_cvt_pk_bf16_f32 v104, v104, v105
	v_add_f32_e32 v105, 0, v106
	v_add_f32_e32 v106, 0, v107
	v_cvt_pk_bf16_f32 v105, v105, v106
	v_add_f32_e32 v106, 0, v116
	v_add_f32_e32 v107, 0, v117
	global_store_dwordx2 v[140:141], v[104:105], off offset:288
	v_cvt_pk_bf16_f32 v106, v106, v107
	v_add_f32_e32 v107, 0, v118
	v_add_f32_e32 v112, 0, v119
	v_cvt_pk_bf16_f32 v107, v107, v112
	v_add_co_u32_e32 v112, vcc, s58, v140
	v_lshl_add_u64 v[104:105], v[140:141], 0, s[24:25]
	s_nop 0
	v_addc_co_u32_e32 v113, vcc, 0, v141, vcc
	global_store_dwordx2 v[112:113], v[106:107], off
	v_add_f32_e32 v106, 0, v108
	v_add_f32_e32 v107, 0, v109
	v_cvt_pk_bf16_f32 v106, v106, v107
	v_add_f32_e32 v107, 0, v110
	v_add_f32_e32 v96, 0, v96
	v_add_f32_e32 v97, 0, v97
	v_add_f32_e32 v108, 0, v111
	v_cvt_pk_bf16_f32 v107, v107, v108
	global_store_dwordx2 v[104:105], v[106:107], off offset:32
	v_cvt_pk_bf16_f32 v96, v96, v97
	v_add_f32_e32 v97, 0, v98
	v_add_f32_e32 v88, 0, v88
	v_add_f32_e32 v89, 0, v89
	v_add_f32_e32 v98, 0, v99
	v_cvt_pk_bf16_f32 v97, v97, v98
	global_store_dwordx2 v[104:105], v[96:97], off offset:256
	v_cvt_pk_bf16_f32 v88, v88, v89
	v_add_f32_e32 v89, 0, v90
	v_add_f32_e32 v90, 0, v91
	v_cvt_pk_bf16_f32 v89, v89, v90
	v_add_f32_e32 v90, 0, v100
	v_add_f32_e32 v91, 0, v101
	global_store_dwordx2 v[104:105], v[88:89], off offset:288
	v_cvt_pk_bf16_f32 v90, v90, v91
	v_add_f32_e32 v91, 0, v102
	v_add_f32_e32 v96, 0, v103
	v_cvt_pk_bf16_f32 v91, v91, v96
	v_add_co_u32_e32 v96, vcc, s67, v140
	v_lshl_add_u64 v[88:89], v[140:141], 0, s[26:27]
	s_nop 0
	v_addc_co_u32_e32 v97, vcc, 0, v141, vcc
	global_store_dwordx2 v[96:97], v[90:91], off
	v_add_f32_e32 v90, 0, v92
	v_add_f32_e32 v91, 0, v93
	v_cvt_pk_bf16_f32 v90, v90, v91
	v_add_f32_e32 v91, 0, v94
	v_add_f32_e32 v80, 0, v80
	v_add_f32_e32 v81, 0, v81
	v_add_f32_e32 v92, 0, v95
	v_cvt_pk_bf16_f32 v91, v91, v92
	global_store_dwordx2 v[88:89], v[90:91], off offset:32
	v_cvt_pk_bf16_f32 v80, v80, v81
	v_add_f32_e32 v81, 0, v82
	v_add_f32_e32 v72, 0, v72
	v_add_f32_e32 v73, 0, v73
	v_add_f32_e32 v82, 0, v83
	v_cvt_pk_bf16_f32 v81, v81, v82
	global_store_dwordx2 v[88:89], v[80:81], off offset:256
	v_cvt_pk_bf16_f32 v72, v72, v73
	v_add_f32_e32 v73, 0, v74
	v_add_f32_e32 v74, 0, v75
	v_cvt_pk_bf16_f32 v73, v73, v74
	v_add_f32_e32 v74, 0, v84
	v_add_f32_e32 v75, 0, v85
	global_store_dwordx2 v[88:89], v[72:73], off offset:288
	v_cvt_pk_bf16_f32 v74, v74, v75
	v_add_f32_e32 v75, 0, v86
	v_add_f32_e32 v80, 0, v87
	v_cvt_pk_bf16_f32 v75, v75, v80
	v_add_co_u32_e32 v80, vcc, s68, v140
	v_lshl_add_u64 v[72:73], v[140:141], 0, s[28:29]
	s_nop 0
	v_addc_co_u32_e32 v81, vcc, 0, v141, vcc
	global_store_dwordx2 v[80:81], v[74:75], off
	v_add_f32_e32 v74, 0, v76
	v_add_f32_e32 v75, 0, v77
	v_cvt_pk_bf16_f32 v74, v74, v75
	v_add_f32_e32 v75, 0, v78
	v_add_f32_e32 v68, 0, v68
	v_add_f32_e32 v69, 0, v69
	v_add_f32_e32 v76, 0, v79
	v_cvt_pk_bf16_f32 v75, v75, v76
	global_store_dwordx2 v[72:73], v[74:75], off offset:32
	v_cvt_pk_bf16_f32 v68, v68, v69
	v_add_f32_e32 v69, 0, v70
	v_add_f32_e32 v64, 0, v64
	v_add_f32_e32 v65, 0, v65
	v_add_f32_e32 v70, 0, v71
	v_cvt_pk_bf16_f32 v69, v69, v70
	global_store_dwordx2 v[72:73], v[68:69], off offset:256
	v_cvt_pk_bf16_f32 v64, v64, v65
	v_add_f32_e32 v65, 0, v66
	v_add_f32_e32 v60, 0, v60
	v_add_f32_e32 v61, 0, v61
	v_add_f32_e32 v66, 0, v67
	v_cvt_pk_bf16_f32 v65, v65, v66
	global_store_dwordx2 v[72:73], v[64:65], off offset:288
	v_cvt_pk_bf16_f32 v60, v60, v61
	v_add_f32_e32 v61, 0, v62
	v_add_f32_e32 v62, 0, v63
	v_cvt_pk_bf16_f32 v61, v61, v62
	v_add_co_u32_e32 v62, vcc, s69, v140
	v_add_f32_e32 v56, 0, v56
	s_nop 0
	v_addc_co_u32_e32 v63, vcc, 0, v141, vcc
	v_add_f32_e32 v57, 0, v57
	v_lshl_add_u64 v[64:65], v[140:141], 0, s[30:31]
	global_store_dwordx2 v[62:63], v[60:61], off
	v_cvt_pk_bf16_f32 v56, v56, v57
	v_add_f32_e32 v57, 0, v58
	v_add_f32_e32 v48, 0, v48
	v_add_f32_e32 v49, 0, v49
	v_add_f32_e32 v58, 0, v59
	v_cvt_pk_bf16_f32 v57, v57, v58
	global_store_dwordx2 v[64:65], v[56:57], off offset:32
	v_cvt_pk_bf16_f32 v48, v48, v49
	v_add_f32_e32 v49, 0, v50
	v_add_f32_e32 v40, 0, v40
	v_add_f32_e32 v41, 0, v41
	v_add_f32_e32 v50, 0, v51
	v_cvt_pk_bf16_f32 v49, v49, v50
	global_store_dwordx2 v[64:65], v[48:49], off offset:256
	v_cvt_pk_bf16_f32 v40, v40, v41
	v_add_f32_e32 v41, 0, v42
	v_add_f32_e32 v42, 0, v43
	v_cvt_pk_bf16_f32 v41, v41, v42
	v_add_f32_e32 v42, 0, v52
	v_add_f32_e32 v43, 0, v53
	global_store_dwordx2 v[64:65], v[40:41], off offset:288
	v_cvt_pk_bf16_f32 v42, v42, v43
	v_add_f32_e32 v43, 0, v54
	v_add_f32_e32 v48, 0, v55
	v_cvt_pk_bf16_f32 v43, v43, v48
	v_add_co_u32_e32 v48, vcc, s70, v140
	v_lshl_add_u64 v[40:41], v[140:141], 0, s[34:35]
	s_nop 0
	v_addc_co_u32_e32 v49, vcc, 0, v141, vcc
	global_store_dwordx2 v[48:49], v[42:43], off
	v_add_f32_e32 v42, 0, v44
	v_add_f32_e32 v43, 0, v45
	v_cvt_pk_bf16_f32 v42, v42, v43
	v_add_f32_e32 v43, 0, v46
	v_add_f32_e32 v32, 0, v32
	v_add_f32_e32 v33, 0, v33
	v_add_f32_e32 v44, 0, v47
	v_cvt_pk_bf16_f32 v43, v43, v44
	global_store_dwordx2 v[40:41], v[42:43], off offset:32
	v_cvt_pk_bf16_f32 v32, v32, v33
	v_add_f32_e32 v33, 0, v34
	v_add_f32_e32 v24, 0, v24
	v_add_f32_e32 v25, 0, v25
	v_add_f32_e32 v34, 0, v35
	v_cvt_pk_bf16_f32 v33, v33, v34
	global_store_dwordx2 v[40:41], v[32:33], off offset:256
	v_cvt_pk_bf16_f32 v24, v24, v25
	v_add_f32_e32 v25, 0, v26
	v_add_f32_e32 v26, 0, v27
	v_cvt_pk_bf16_f32 v25, v25, v26
	v_add_f32_e32 v26, 0, v36
	v_add_f32_e32 v27, 0, v37
	global_store_dwordx2 v[40:41], v[24:25], off offset:288
	v_cvt_pk_bf16_f32 v26, v26, v27
	v_add_f32_e32 v27, 0, v38
	v_add_f32_e32 v32, 0, v39
	v_cvt_pk_bf16_f32 v27, v27, v32
	v_add_co_u32_e32 v32, vcc, s71, v140
	v_lshl_add_u64 v[24:25], v[140:141], 0, s[36:37]
	s_nop 0
	v_addc_co_u32_e32 v33, vcc, 0, v141, vcc
	global_store_dwordx2 v[32:33], v[26:27], off
	v_add_f32_e32 v26, 0, v28
	v_add_f32_e32 v27, 0, v29
	v_cvt_pk_bf16_f32 v26, v26, v27
	v_add_f32_e32 v27, 0, v30
	v_add_f32_e32 v16, 0, v16
	v_add_f32_e32 v17, 0, v17
	v_add_f32_e32 v28, 0, v31
	v_cvt_pk_bf16_f32 v27, v27, v28
	global_store_dwordx2 v[24:25], v[26:27], off offset:32
	v_cvt_pk_bf16_f32 v16, v16, v17
	v_add_f32_e32 v17, 0, v18
	v_add_f32_e32 v8, 0, v8
	v_add_f32_e32 v9, 0, v9
	v_add_f32_e32 v18, 0, v19
	v_cvt_pk_bf16_f32 v17, v17, v18
	global_store_dwordx2 v[24:25], v[16:17], off offset:256
	v_cvt_pk_bf16_f32 v8, v8, v9
	v_add_f32_e32 v9, 0, v10
	v_add_f32_e32 v10, 0, v11
	v_cvt_pk_bf16_f32 v9, v9, v10
	v_add_f32_e32 v10, 0, v20
	v_add_f32_e32 v11, 0, v21
	global_store_dwordx2 v[24:25], v[8:9], off offset:288
	v_cvt_pk_bf16_f32 v10, v10, v11
	v_add_f32_e32 v11, 0, v22
	v_add_f32_e32 v16, 0, v23
	v_cvt_pk_bf16_f32 v11, v11, v16
	v_add_co_u32_e32 v16, vcc, s72, v140
	v_lshl_add_u64 v[8:9], v[140:141], 0, s[42:43]
	s_nop 0
	v_addc_co_u32_e32 v17, vcc, 0, v141, vcc
	global_store_dwordx2 v[16:17], v[10:11], off
	v_add_f32_e32 v10, 0, v12
	v_add_f32_e32 v11, 0, v13
	v_cvt_pk_bf16_f32 v10, v10, v11
	v_add_f32_e32 v11, 0, v14
	v_add_f32_e32 v4, 0, v4
	v_add_f32_e32 v5, 0, v5
	v_add_f32_e32 v12, 0, v15
	v_cvt_pk_bf16_f32 v11, v11, v12
	global_store_dwordx2 v[8:9], v[10:11], off offset:32
	v_cvt_pk_bf16_f32 v4, v4, v5
	v_add_f32_e32 v5, 0, v6
	v_add_f32_e32 v0, 0, v0
	v_add_f32_e32 v1, 0, v1
	v_add_f32_e32 v6, 0, v7
	v_cvt_pk_bf16_f32 v5, v5, v6
	global_store_dwordx2 v[8:9], v[4:5], off offset:256
	v_cvt_pk_bf16_f32 v0, v0, v1
	v_add_f32_e32 v1, 0, v2
	v_add_f32_e32 v2, 0, v3
	v_cvt_pk_bf16_f32 v1, v1, v2
	global_store_dwordx2 v[8:9], v[0:1], off offset:288
	s_and_b64 vcc, exec, s[4:5]
	s_mov_b32 s74, s73
	v_mov_b32_e32 v140, v142
	v_mov_b64_e32 v[0:1], v[144:145]
	v_mov_b64_e32 v[2:3], v[146:147]
	s_mov_b32 s90, s91
	s_cbranch_vccz .LBB0_1821
	s_branch .Lts_b_after

.Lts_b_e0:
	v_add_u32_e32 v140, v140, v154
	v_ashrrev_i32_e32 v141, 31, v140
	v_add_u32_e32 v148, s74, v156
	v_lshlrev_b64 v[140:141], 12, v[140:141]
	v_ashrrev_i32_e32 v149, 31, v148
	v_lshl_add_u64 v[140:141], s[14:15], 0, v[140:141]
	v_add_f32_e32 v124, 0, v124
	v_add_f32_e32 v125, 0, v125
	v_lshl_add_u64 v[140:141], v[148:149], 1, v[140:141]
	v_cvt_pk_bf16_f32 v124, v124, v125
	v_add_f32_e32 v125, 0, v126
	v_add_f32_e32 v120, 0, v120
	v_add_f32_e32 v121, 0, v121
	v_add_f32_e32 v126, 0, v127
	v_cvt_pk_bf16_f32 v125, v125, v126
	global_store_dwordx2 v[140:141], v[124:125], off
	v_cvt_pk_bf16_f32 v120, v120, v121
	v_add_f32_e32 v121, 0, v122
	v_add_f32_e32 v112, 0, v112
	v_add_f32_e32 v113, 0, v113
	v_add_f32_e32 v122, 0, v123
	v_cvt_pk_bf16_f32 v121, v121, v122
	global_store_dwordx2 v[140:141], v[120:121], off offset:32
	v_cvt_pk_bf16_f32 v112, v112, v113
	v_add_f32_e32 v113, 0, v114
	v_add_f32_e32 v104, 0, v104
	v_add_f32_e32 v105, 0, v105
	v_add_f32_e32 v114, 0, v115
	v_cvt_pk_bf16_f32 v113, v113, v114
	global_store_dwordx2 v[140:141], v[112:113], off offset:256
	v_cvt_pk_bf16_f32 v104, v104, v105
	v_add_f32_e32 v105, 0, v106
	v_add_f32_e32 v106, 0, v107
	v_cvt_pk_bf16_f32 v105, v105, v106
	v_add_f32_e32 v106, 0, v116
	v_add_f32_e32 v107, 0, v117
	global_store_dwordx2 v[140:141], v[104:105], off offset:288
	v_cvt_pk_bf16_f32 v106, v106, v107
	v_add_f32_e32 v107, 0, v118
	v_add_f32_e32 v112, 0, v119
	v_cvt_pk_bf16_f32 v107, v107, v112
	v_add_co_u32_e32 v112, vcc, s58, v140
	v_lshl_add_u64 v[104:105], v[140:141], 0, s[24:25]
	s_nop 0
	v_addc_co_u32_e32 v113, vcc, 0, v141, vcc
	global_store_dwordx2 v[112:113], v[106:107], off
	v_add_f32_e32 v106, 0, v108
	v_add_f32_e32 v107, 0, v109
	v_cvt_pk_bf16_f32 v106, v106, v107
	v_add_f32_e32 v107, 0, v110
	v_add_f32_e32 v96, 0, v96
	v_add_f32_e32 v97, 0, v97
	v_add_f32_e32 v108, 0, v111
	v_cvt_pk_bf16_f32 v107, v107, v108
	global_store_dwordx2 v[104:105], v[106:107], off offset:32
	v_cvt_pk_bf16_f32 v96, v96, v97
	v_add_f32_e32 v97, 0, v98
	v_add_f32_e32 v88, 0, v88
	v_add_f32_e32 v89, 0, v89
	v_add_f32_e32 v98, 0, v99
	v_cvt_pk_bf16_f32 v97, v97, v98
	global_store_dwordx2 v[104:105], v[96:97], off offset:256
	v_cvt_pk_bf16_f32 v88, v88, v89
	v_add_f32_e32 v89, 0, v90
	v_add_f32_e32 v90, 0, v91
	v_cvt_pk_bf16_f32 v89, v89, v90
	v_add_f32_e32 v90, 0, v100
	v_add_f32_e32 v91, 0, v101
	global_store_dwordx2 v[104:105], v[88:89], off offset:288
	v_cvt_pk_bf16_f32 v90, v90, v91
	v_add_f32_e32 v91, 0, v102
	v_add_f32_e32 v96, 0, v103
	v_cvt_pk_bf16_f32 v91, v91, v96
	v_add_co_u32_e32 v96, vcc, s67, v140
	v_lshl_add_u64 v[88:89], v[140:141], 0, s[26:27]
	s_nop 0
	v_addc_co_u32_e32 v97, vcc, 0, v141, vcc
	global_store_dwordx2 v[96:97], v[90:91], off
	v_add_f32_e32 v90, 0, v92
	v_add_f32_e32 v91, 0, v93
	v_cvt_pk_bf16_f32 v90, v90, v91
	v_add_f32_e32 v91, 0, v94
	v_add_f32_e32 v80, 0, v80
	v_add_f32_e32 v81, 0, v81
	v_add_f32_e32 v92, 0, v95
	v_cvt_pk_bf16_f32 v91, v91, v92
	global_store_dwordx2 v[88:89], v[90:91], off offset:32
	v_cvt_pk_bf16_f32 v80, v80, v81
	v_add_f32_e32 v81, 0, v82
	v_add_f32_e32 v72, 0, v72
	v_add_f32_e32 v73, 0, v73
	v_add_f32_e32 v82, 0, v83
	v_cvt_pk_bf16_f32 v81, v81, v82
	global_store_dwordx2 v[88:89], v[80:81], off offset:256
	v_cvt_pk_bf16_f32 v72, v72, v73
	v_add_f32_e32 v73, 0, v74
	v_add_f32_e32 v74, 0, v75
	v_cvt_pk_bf16_f32 v73, v73, v74
	v_add_f32_e32 v74, 0, v84
	v_add_f32_e32 v75, 0, v85
	global_store_dwordx2 v[88:89], v[72:73], off offset:288
	v_cvt_pk_bf16_f32 v74, v74, v75
	v_add_f32_e32 v75, 0, v86
	v_add_f32_e32 v80, 0, v87
	v_cvt_pk_bf16_f32 v75, v75, v80
	v_add_co_u32_e32 v80, vcc, s68, v140
	v_lshl_add_u64 v[72:73], v[140:141], 0, s[28:29]
	s_nop 0
	v_addc_co_u32_e32 v81, vcc, 0, v141, vcc
	global_store_dwordx2 v[80:81], v[74:75], off
	v_add_f32_e32 v74, 0, v76
	v_add_f32_e32 v75, 0, v77
	v_cvt_pk_bf16_f32 v74, v74, v75
	v_add_f32_e32 v75, 0, v78
	v_add_f32_e32 v68, 0, v68
	v_add_f32_e32 v69, 0, v69
	v_add_f32_e32 v76, 0, v79
	v_cvt_pk_bf16_f32 v75, v75, v76
	global_store_dwordx2 v[72:73], v[74:75], off offset:32
	v_cvt_pk_bf16_f32 v68, v68, v69
	v_add_f32_e32 v69, 0, v70
	v_add_f32_e32 v64, 0, v64
	v_add_f32_e32 v65, 0, v65
	v_add_f32_e32 v70, 0, v71
	v_cvt_pk_bf16_f32 v69, v69, v70
	global_store_dwordx2 v[72:73], v[68:69], off offset:256
	v_cvt_pk_bf16_f32 v64, v64, v65
	v_add_f32_e32 v65, 0, v66
	v_add_f32_e32 v60, 0, v60
	v_add_f32_e32 v61, 0, v61
	v_add_f32_e32 v66, 0, v67
	v_cvt_pk_bf16_f32 v65, v65, v66
	global_store_dwordx2 v[72:73], v[64:65], off offset:288
	v_cvt_pk_bf16_f32 v60, v60, v61
	v_add_f32_e32 v61, 0, v62
	v_add_f32_e32 v62, 0, v63
	v_cvt_pk_bf16_f32 v61, v61, v62
	v_add_co_u32_e32 v62, vcc, s69, v140
	v_add_f32_e32 v56, 0, v56
	s_nop 0
	v_addc_co_u32_e32 v63, vcc, 0, v141, vcc
	v_add_f32_e32 v57, 0, v57
	v_lshl_add_u64 v[64:65], v[140:141], 0, s[30:31]
	s_nop 0
	v_cvt_pk_bf16_f32 v56, v56, v57
	v_add_f32_e32 v57, 0, v58
	v_add_f32_e32 v48, 0, v48
	v_add_f32_e32 v49, 0, v49
	v_add_f32_e32 v58, 0, v59
	v_cvt_pk_bf16_f32 v57, v57, v58
	s_nop 0
	v_cvt_pk_bf16_f32 v48, v48, v49
	v_add_f32_e32 v49, 0, v50
	v_add_f32_e32 v40, 0, v40
	v_add_f32_e32 v41, 0, v41
	v_add_f32_e32 v50, 0, v51
	v_cvt_pk_bf16_f32 v49, v49, v50
	s_nop 0
	v_cvt_pk_bf16_f32 v40, v40, v41
	v_add_f32_e32 v41, 0, v42
	v_add_f32_e32 v42, 0, v43
	v_cvt_pk_bf16_f32 v41, v41, v42
	v_add_f32_e32 v42, 0, v52
	v_add_f32_e32 v43, 0, v53
	s_nop 0
	v_cvt_pk_bf16_f32 v42, v42, v43
	v_add_f32_e32 v43, 0, v54
	v_add_f32_e32 v48, 0, v55
	v_cvt_pk_bf16_f32 v43, v43, v48
	v_add_co_u32_e32 v48, vcc, s70, v140
	v_lshl_add_u64 v[40:41], v[140:141], 0, s[34:35]
	s_nop 0
	v_addc_co_u32_e32 v49, vcc, 0, v141, vcc
	s_nop 0
	v_add_f32_e32 v42, 0, v44
	v_add_f32_e32 v43, 0, v45
	v_cvt_pk_bf16_f32 v42, v42, v43
	v_add_f32_e32 v43, 0, v46
	v_add_f32_e32 v32, 0, v32
	v_add_f32_e32 v33, 0, v33
	v_add_f32_e32 v44, 0, v47
	v_cvt_pk_bf16_f32 v43, v43, v44
	s_nop 0
	v_cvt_pk_bf16_f32 v32, v32, v33
	v_add_f32_e32 v33, 0, v34
	v_add_f32_e32 v24, 0, v24
	v_add_f32_e32 v25, 0, v25
	v_add_f32_e32 v34, 0, v35
	v_cvt_pk_bf16_f32 v33, v33, v34
	s_nop 0
	v_cvt_pk_bf16_f32 v24, v24, v25
	v_add_f32_e32 v25, 0, v26
	v_add_f32_e32 v26, 0, v27
	v_cvt_pk_bf16_f32 v25, v25, v26
	v_add_f32_e32 v26, 0, v36
	v_add_f32_e32 v27, 0, v37
	s_nop 0
	v_cvt_pk_bf16_f32 v26, v26, v27
	v_add_f32_e32 v27, 0, v38
	v_add_f32_e32 v32, 0, v39
	v_cvt_pk_bf16_f32 v27, v27, v32
	v_add_co_u32_e32 v32, vcc, s71, v140
	v_lshl_add_u64 v[24:25], v[140:141], 0, s[36:37]
	s_nop 0
	v_addc_co_u32_e32 v33, vcc, 0, v141, vcc
	s_nop 0
	v_add_f32_e32 v26, 0, v28
	v_add_f32_e32 v27, 0, v29
	v_cvt_pk_bf16_f32 v26, v26, v27
	v_add_f32_e32 v27, 0, v30
	v_add_f32_e32 v16, 0, v16
	v_add_f32_e32 v17, 0, v17
	v_add_f32_e32 v28, 0, v31
	v_cvt_pk_bf16_f32 v27, v27, v28
	s_nop 0
	v_cvt_pk_bf16_f32 v16, v16, v17
	v_add_f32_e32 v17, 0, v18
	v_add_f32_e32 v8, 0, v8
	v_add_f32_e32 v9, 0, v9
	v_add_f32_e32 v18, 0, v19
	v_cvt_pk_bf16_f32 v17, v17, v18
	s_nop 0
	v_cvt_pk_bf16_f32 v8, v8, v9
	v_add_f32_e32 v9, 0, v10
	v_add_f32_e32 v10, 0, v11
	v_cvt_pk_bf16_f32 v9, v9, v10
	v_add_f32_e32 v10, 0, v20
	v_add_f32_e32 v11, 0, v21
	s_nop 0
	v_cvt_pk_bf16_f32 v10, v10, v11
	v_add_f32_e32 v11, 0, v22
	v_add_f32_e32 v16, 0, v23
	v_cvt_pk_bf16_f32 v11, v11, v16
	v_add_co_u32_e32 v16, vcc, s72, v140
	v_lshl_add_u64 v[8:9], v[140:141], 0, s[42:43]
	s_nop 0
	v_addc_co_u32_e32 v17, vcc, 0, v141, vcc
	s_nop 0
	v_add_f32_e32 v10, 0, v12
	v_add_f32_e32 v11, 0, v13
	v_cvt_pk_bf16_f32 v10, v10, v11
	v_add_f32_e32 v11, 0, v14
	v_add_f32_e32 v4, 0, v4
	v_add_f32_e32 v5, 0, v5
	v_add_f32_e32 v12, 0, v15
	v_cvt_pk_bf16_f32 v11, v11, v12
	s_nop 0
	v_cvt_pk_bf16_f32 v4, v4, v5
	v_add_f32_e32 v5, 0, v6
	v_add_f32_e32 v0, 0, v0
	v_add_f32_e32 v1, 0, v1
	v_add_f32_e32 v6, 0, v7
	v_cvt_pk_bf16_f32 v5, v5, v6
	s_nop 0
	v_cvt_pk_bf16_f32 v0, v0, v1
	v_add_f32_e32 v1, 0, v2
	v_add_f32_e32 v2, 0, v3
	v_cvt_pk_bf16_f32 v1, v1, v2
	s_nop 0
	s_and_b64 vcc, exec, s[4:5]
	s_mov_b32 s74, s73
	v_mov_b32_e32 v140, v142
	v_mov_b64_e32 v[0:1], v[144:145]
	v_mov_b64_e32 v[2:3], v[146:147]
	s_branch .Lts_b_after

.Lts_b_e1:
	v_add_u32_e32 v140, v140, v154
	v_ashrrev_i32_e32 v141, 31, v140
	v_add_u32_e32 v148, s74, v156
	v_lshlrev_b64 v[140:141], 12, v[140:141]
	v_ashrrev_i32_e32 v149, 31, v148
	v_lshl_add_u64 v[140:141], s[14:15], 0, v[140:141]
	v_add_f32_e32 v124, 0, v124
	v_add_f32_e32 v125, 0, v125
	v_lshl_add_u64 v[140:141], v[148:149], 1, v[140:141]
	v_cvt_pk_bf16_f32 v124, v124, v125
	v_add_f32_e32 v125, 0, v126
	v_add_f32_e32 v120, 0, v120
	v_add_f32_e32 v121, 0, v121
	v_add_f32_e32 v126, 0, v127
	v_cvt_pk_bf16_f32 v125, v125, v126
	s_nop 0
	v_cvt_pk_bf16_f32 v120, v120, v121
	v_add_f32_e32 v121, 0, v122
	v_add_f32_e32 v112, 0, v112
	v_add_f32_e32 v113, 0, v113
	v_add_f32_e32 v122, 0, v123
	v_cvt_pk_bf16_f32 v121, v121, v122
	s_nop 0
	v_cvt_pk_bf16_f32 v112, v112, v113
	v_add_f32_e32 v113, 0, v114
	v_add_f32_e32 v104, 0, v104
	v_add_f32_e32 v105, 0, v105
	v_add_f32_e32 v114, 0, v115
	v_cvt_pk_bf16_f32 v113, v113, v114
	s_nop 0
	v_cvt_pk_bf16_f32 v104, v104, v105
	v_add_f32_e32 v105, 0, v106
	v_add_f32_e32 v106, 0, v107
	v_cvt_pk_bf16_f32 v105, v105, v106
	v_add_f32_e32 v106, 0, v116
	v_add_f32_e32 v107, 0, v117
	s_nop 0
	v_cvt_pk_bf16_f32 v106, v106, v107
	v_add_f32_e32 v107, 0, v118
	v_add_f32_e32 v112, 0, v119
	v_cvt_pk_bf16_f32 v107, v107, v112
	v_add_co_u32_e32 v112, vcc, s58, v140
	v_lshl_add_u64 v[104:105], v[140:141], 0, s[24:25]
	s_nop 0
	v_addc_co_u32_e32 v113, vcc, 0, v141, vcc
	s_nop 0
	v_add_f32_e32 v106, 0, v108
	v_add_f32_e32 v107, 0, v109
	v_cvt_pk_bf16_f32 v106, v106, v107
	v_add_f32_e32 v107, 0, v110
	v_add_f32_e32 v96, 0, v96
	v_add_f32_e32 v97, 0, v97
	v_add_f32_e32 v108, 0, v111
	v_cvt_pk_bf16_f32 v107, v107, v108
	s_nop 0
	v_cvt_pk_bf16_f32 v96, v96, v97
	v_add_f32_e32 v97, 0, v98
	v_add_f32_e32 v88, 0, v88
	v_add_f32_e32 v89, 0, v89
	v_add_f32_e32 v98, 0, v99
	v_cvt_pk_bf16_f32 v97, v97, v98
	s_nop 0
	v_cvt_pk_bf16_f32 v88, v88, v89
	v_add_f32_e32 v89, 0, v90
	v_add_f32_e32 v90, 0, v91
	v_cvt_pk_bf16_f32 v89, v89, v90
	v_add_f32_e32 v90, 0, v100
	v_add_f32_e32 v91, 0, v101
	s_nop 0
	v_cvt_pk_bf16_f32 v90, v90, v91
	v_add_f32_e32 v91, 0, v102
	v_add_f32_e32 v96, 0, v103
	v_cvt_pk_bf16_f32 v91, v91, v96
	v_add_co_u32_e32 v96, vcc, s67, v140
	v_lshl_add_u64 v[88:89], v[140:141], 0, s[26:27]
	s_nop 0
	v_addc_co_u32_e32 v97, vcc, 0, v141, vcc
	s_nop 0
	v_add_f32_e32 v90, 0, v92
	v_add_f32_e32 v91, 0, v93
	v_cvt_pk_bf16_f32 v90, v90, v91
	v_add_f32_e32 v91, 0, v94
	v_add_f32_e32 v80, 0, v80
	v_add_f32_e32 v81, 0, v81
	v_add_f32_e32 v92, 0, v95
	v_cvt_pk_bf16_f32 v91, v91, v92
	s_nop 0
	v_cvt_pk_bf16_f32 v80, v80, v81
	v_add_f32_e32 v81, 0, v82
	v_add_f32_e32 v72, 0, v72
	v_add_f32_e32 v73, 0, v73
	v_add_f32_e32 v82, 0, v83
	v_cvt_pk_bf16_f32 v81, v81, v82
	s_nop 0
	v_cvt_pk_bf16_f32 v72, v72, v73
	v_add_f32_e32 v73, 0, v74
	v_add_f32_e32 v74, 0, v75
	v_cvt_pk_bf16_f32 v73, v73, v74
	v_add_f32_e32 v74, 0, v84
	v_add_f32_e32 v75, 0, v85
	s_nop 0
	v_cvt_pk_bf16_f32 v74, v74, v75
	v_add_f32_e32 v75, 0, v86
	v_add_f32_e32 v80, 0, v87
	v_cvt_pk_bf16_f32 v75, v75, v80
	v_add_co_u32_e32 v80, vcc, s68, v140
	v_lshl_add_u64 v[72:73], v[140:141], 0, s[28:29]
	s_nop 0
	v_addc_co_u32_e32 v81, vcc, 0, v141, vcc
	s_nop 0
	v_add_f32_e32 v74, 0, v76
	v_add_f32_e32 v75, 0, v77
	v_cvt_pk_bf16_f32 v74, v74, v75
	v_add_f32_e32 v75, 0, v78
	v_add_f32_e32 v68, 0, v68
	v_add_f32_e32 v69, 0, v69
	v_add_f32_e32 v76, 0, v79
	v_cvt_pk_bf16_f32 v75, v75, v76
	s_nop 0
	v_cvt_pk_bf16_f32 v68, v68, v69
	v_add_f32_e32 v69, 0, v70
	v_add_f32_e32 v64, 0, v64
	v_add_f32_e32 v65, 0, v65
	v_add_f32_e32 v70, 0, v71
	v_cvt_pk_bf16_f32 v69, v69, v70
	s_nop 0
	v_cvt_pk_bf16_f32 v64, v64, v65
	v_add_f32_e32 v65, 0, v66
	v_add_f32_e32 v60, 0, v60
	v_add_f32_e32 v61, 0, v61
	v_add_f32_e32 v66, 0, v67
	v_cvt_pk_bf16_f32 v65, v65, v66
	s_nop 0
	v_cvt_pk_bf16_f32 v60, v60, v61
	v_add_f32_e32 v61, 0, v62
	v_add_f32_e32 v62, 0, v63
	v_cvt_pk_bf16_f32 v61, v61, v62
	v_add_co_u32_e32 v62, vcc, s69, v140
	v_add_f32_e32 v56, 0, v56
	s_nop 0
	v_addc_co_u32_e32 v63, vcc, 0, v141, vcc
	v_add_f32_e32 v57, 0, v57
	v_lshl_add_u64 v[64:65], v[140:141], 0, s[30:31]
	global_store_dwordx2 v[62:63], v[60:61], off
	v_cvt_pk_bf16_f32 v56, v56, v57
	v_add_f32_e32 v57, 0, v58
	v_add_f32_e32 v48, 0, v48
	v_add_f32_e32 v49, 0, v49
	v_add_f32_e32 v58, 0, v59
	v_cvt_pk_bf16_f32 v57, v57, v58
	global_store_dwordx2 v[64:65], v[56:57], off offset:32
	v_cvt_pk_bf16_f32 v48, v48, v49
	v_add_f32_e32 v49, 0, v50
	v_add_f32_e32 v40, 0, v40
	v_add_f32_e32 v41, 0, v41
	v_add_f32_e32 v50, 0, v51
	v_cvt_pk_bf16_f32 v49, v49, v50
	global_store_dwordx2 v[64:65], v[48:49], off offset:256
	v_cvt_pk_bf16_f32 v40, v40, v41
	v_add_f32_e32 v41, 0, v42
	v_add_f32_e32 v42, 0, v43
	v_cvt_pk_bf16_f32 v41, v41, v42
	v_add_f32_e32 v42, 0, v52
	v_add_f32_e32 v43, 0, v53
	global_store_dwordx2 v[64:65], v[40:41], off offset:288
	v_cvt_pk_bf16_f32 v42, v42, v43
	v_add_f32_e32 v43, 0, v54
	v_add_f32_e32 v48, 0, v55
	v_cvt_pk_bf16_f32 v43, v43, v48
	v_add_co_u32_e32 v48, vcc, s70, v140
	v_lshl_add_u64 v[40:41], v[140:141], 0, s[34:35]
	s_nop 0
	v_addc_co_u32_e32 v49, vcc, 0, v141, vcc
	global_store_dwordx2 v[48:49], v[42:43], off
	v_add_f32_e32 v42, 0, v44
	v_add_f32_e32 v43, 0, v45
	v_cvt_pk_bf16_f32 v42, v42, v43
	v_add_f32_e32 v43, 0, v46
	v_add_f32_e32 v32, 0, v32
	v_add_f32_e32 v33, 0, v33
	v_add_f32_e32 v44, 0, v47
	v_cvt_pk_bf16_f32 v43, v43, v44
	global_store_dwordx2 v[40:41], v[42:43], off offset:32
	v_cvt_pk_bf16_f32 v32, v32, v33
	v_add_f32_e32 v33, 0, v34
	v_add_f32_e32 v24, 0, v24
	v_add_f32_e32 v25, 0, v25
	v_add_f32_e32 v34, 0, v35
	v_cvt_pk_bf16_f32 v33, v33, v34
	global_store_dwordx2 v[40:41], v[32:33], off offset:256
	v_cvt_pk_bf16_f32 v24, v24, v25
	v_add_f32_e32 v25, 0, v26
	v_add_f32_e32 v26, 0, v27
	v_cvt_pk_bf16_f32 v25, v25, v26
	v_add_f32_e32 v26, 0, v36
	v_add_f32_e32 v27, 0, v37
	global_store_dwordx2 v[40:41], v[24:25], off offset:288
	v_cvt_pk_bf16_f32 v26, v26, v27
	v_add_f32_e32 v27, 0, v38
	v_add_f32_e32 v32, 0, v39
	v_cvt_pk_bf16_f32 v27, v27, v32
	v_add_co_u32_e32 v32, vcc, s71, v140
	v_lshl_add_u64 v[24:25], v[140:141], 0, s[36:37]
	s_nop 0
	v_addc_co_u32_e32 v33, vcc, 0, v141, vcc
	global_store_dwordx2 v[32:33], v[26:27], off
	v_add_f32_e32 v26, 0, v28
	v_add_f32_e32 v27, 0, v29
	v_cvt_pk_bf16_f32 v26, v26, v27
	v_add_f32_e32 v27, 0, v30
	v_add_f32_e32 v16, 0, v16
	v_add_f32_e32 v17, 0, v17
	v_add_f32_e32 v28, 0, v31
	v_cvt_pk_bf16_f32 v27, v27, v28
	global_store_dwordx2 v[24:25], v[26:27], off offset:32
	v_cvt_pk_bf16_f32 v16, v16, v17
	v_add_f32_e32 v17, 0, v18
	v_add_f32_e32 v8, 0, v8
	v_add_f32_e32 v9, 0, v9
	v_add_f32_e32 v18, 0, v19
	v_cvt_pk_bf16_f32 v17, v17, v18
	global_store_dwordx2 v[24:25], v[16:17], off offset:256
	v_cvt_pk_bf16_f32 v8, v8, v9
	v_add_f32_e32 v9, 0, v10
	v_add_f32_e32 v10, 0, v11
	v_cvt_pk_bf16_f32 v9, v9, v10
	v_add_f32_e32 v10, 0, v20
	v_add_f32_e32 v11, 0, v21
	global_store_dwordx2 v[24:25], v[8:9], off offset:288
	v_cvt_pk_bf16_f32 v10, v10, v11
	v_add_f32_e32 v11, 0, v22
	v_add_f32_e32 v16, 0, v23
	v_cvt_pk_bf16_f32 v11, v11, v16
	v_add_co_u32_e32 v16, vcc, s72, v140
	v_lshl_add_u64 v[8:9], v[140:141], 0, s[42:43]
	s_nop 0
	v_addc_co_u32_e32 v17, vcc, 0, v141, vcc
	global_store_dwordx2 v[16:17], v[10:11], off
	v_add_f32_e32 v10, 0, v12
	v_add_f32_e32 v11, 0, v13
	v_cvt_pk_bf16_f32 v10, v10, v11
	v_add_f32_e32 v11, 0, v14
	v_add_f32_e32 v4, 0, v4
	v_add_f32_e32 v5, 0, v5
	v_add_f32_e32 v12, 0, v15
	v_cvt_pk_bf16_f32 v11, v11, v12
	global_store_dwordx2 v[8:9], v[10:11], off offset:32
	v_cvt_pk_bf16_f32 v4, v4, v5
	v_add_f32_e32 v5, 0, v6
	v_add_f32_e32 v0, 0, v0
	v_add_f32_e32 v1, 0, v1
	v_add_f32_e32 v6, 0, v7
	v_cvt_pk_bf16_f32 v5, v5, v6
	global_store_dwordx2 v[8:9], v[4:5], off offset:256
	v_cvt_pk_bf16_f32 v0, v0, v1
	v_add_f32_e32 v1, 0, v2
	v_add_f32_e32 v2, 0, v3
	v_cvt_pk_bf16_f32 v1, v1, v2
	global_store_dwordx2 v[8:9], v[0:1], off offset:288
	s_and_b64 vcc, exec, s[4:5]
	s_mov_b32 s74, s73
	v_mov_b32_e32 v140, v142
	v_mov_b64_e32 v[0:1], v[144:145]
	v_mov_b64_e32 v[2:3], v[146:147]
	s_branch .Lts_b_after
